# row-pass counted vmcnt waits on fp16 path + 8x128B LDS-DMA piece layout for EpiBf16 and SwiGLU GEMMs
# speedup vs baseline: 1.0081x; 1.0081x over previous
; #define PG8_STAGE(bufoff, gbase, voff) do { _Pragma("unroll") for (int _i = 0; _i < 2; ++_i) \
;         __builtin_amdgcn_global_load_lds((const unsigned*)((const char*)(gbase) + (voff)[_i]), (PG8_LAS unsigned*)(lds + (bufoff) + ldsw + _i * 8192), 16, 0, 0); } while (0)
; #define PG8_WAIT_V(n) asm volatile("s_waitcnt vmcnt(" #n ")" ::: "memory")
; #define PG8_BAR __builtin_amdgcn_s_barrier()
; template <class Epi, class Sched, bool ALIGN_EPI = false, bool SP2 = false>
; __device__ __forceinline__ void gemm_phase(PG8_LAS unsigned char* lds, const Gemm g, const Sched& S, const Epi& E) {
;     ...
;     for (int i = 0; i < 2; ++i) { int R, C; stage_rc(tid * 16 + i * 8192, R, C); const int Rb = Epi::PERM ? ((R & ~31) + perm32(R & 31)) : R;
;         voffA[i] = (unsigned)(R * K + C) * 2u; voffB[i] = (unsigned)(Rb * K + C) * 2u; }
;     const size_t kstep = (size_t)(BK * 2);
;     const size_t hstep = (size_t)HALF * K * 2;
;     const size_t tstep = 2 * hstep;
;     const unsigned ldsw = (unsigned)wid * 1024u;
;     const int aoff = lds_byte(wr * 64 + fr, fq * 8), boff = lds_byte(wc * 32 + fr, fq * 8);
;     ...
;     Unit cur, nxt; int ui = 0;
;     if (!S.next(0, cur)) return;
;     f32x4 acc[2][2][4][2];
; #pragma unroll
;     for (int a = 0; a < 2; ++a)
; #pragma unroll
;         for (int b = 0; b < 2; ++b)
; #pragma unroll
;             for (int m = 0; m < 4; ++m)
; #pragma unroll
;                 for (int n = 0; n < 2; ++n) acc[a][b][m][n] = (f32x4){0.f, 0.f, 0.f, 0.f};
;     bf16x8 At[4][2], B0[2][2], B1[2][2];
;     const char* cA = (const char*)g.A + (size_t)cur.pm * tstep; const char* cB = (const char*)g.Bt + (size_t)cur.pn * tstep;
;     S.a_ready(cur);
;     if constexpr (SP2) {
;         PG8_STAGE(PG8_SB(0, 0), cB, voffB); PG8_STAGE(PG8_SB(0, 1), cB + hstep, voffB); PG8_STAGE(PG8_SA(0, 0), cA, voffA); PG8_STAGE(PG8_SA(0, 1), cA + hstep, voffA);
;         if (wr == 1) PG8_BAR;
;         PG8_WAIT_V(2); PG8_BAR;
;         PG8_STAGE(PG8_SB(1, 0), cB + kstep, voffB); PG8_STAGE(PG8_SA(1, 0), cA + kstep, voffA); PG8_STAGE(PG8_SB(1, 1), cB + hstep + kstep, voffB);
;         PG8_WAIT_V(6); PG8_BAR;
.LBB0_43:
	v_mov_b32_e32 v2, v228
	s_andn2_b64 vcc, exec, s[44:45]
	v_readfirstlane_b32 s8, v2
	s_cbranch_vccnz .LBB0_27
	v_lshrrev_b32_e32 v242, 3, v228
	v_and_b32_e32 v243, 7, v228
	v_and_b32_e32 v244, 6, v242
	v_xor_b32_e32 v243, v243, v244
	v_lshlrev_b32_e32 v243, 3, v243
	v_mul_lo_u32 v245, v242, s1
	v_add_lshl_u32 v232, v245, v243, 1
	v_add_u32_e32 v246, 64, v242
	v_mul_lo_u32 v246, v246, s1
	v_add_lshl_u32 v233, v246, v243, 1
	v_and_b32_e32 v247, 31, v242
	v_lshrrev_b32_e32 v248, 4, v247
	v_and_b32_e32 v249, 15, v247
	v_lshrrev_b32_e32 v250, 2, v249
	v_lshlrev_b32_e32 v250, 3, v250
	v_and_b32_e32 v249, 3, v249
	v_lshl_add_u32 v250, v248, 2, v250
	v_add_u32_e32 v250, v250, v249
	v_and_b32_e32 v247, 32, v242
	v_add_u32_e32 v250, v250, v247
	v_mul_lo_u32 v251, v250, s1
	v_add_lshl_u32 v236, v251, v243, 1
	v_add_u32_e32 v250, 64, v250
	v_mul_lo_u32 v251, v250, s1
	v_add_lshl_u32 v237, v251, v243, 1
	v_and_b32_e32 v244, 15, v228
	v_bfe_u32 v245, v228, 4, 2
	v_and_b32_e32 v246, 6, v244
	v_xor_b32_e32 v246, v246, v245
	v_lshlrev_b32_e32 v246, 4, v246
	v_and_b32_e32 v247, 7, v244
	v_lshl_add_u32 v246, v247, 7, v246
	v_lshrrev_b32_e32 v247, 3, v244
	v_lshl_add_u32 v246, v247, 10, v246
	v_lshrrev_b32_e32 v247, 8, v228
	v_lshl_add_u32 v227, v247, 13, v246
	v_xor_b32_e32 v225, 64, v227
	v_bfe_u32 v247, v228, 6, 2
	v_lshl_add_u32 v252, v247, 12, v246
	v_xor_b32_e32 v226, 64, v252
	v_lshlrev_b32_e32 v0, 4, v2
	v_add_u32_e32 v3, 0x2000, v0
	v_ashrrev_i32_e32 v4, 31, v3
	v_lshrrev_b32_e32 v4, 22, v4
	v_add_u32_e32 v4, v3, v4
	v_ashrrev_i32_e32 v4, 10, v4
	v_mul_i32_i24_e32 v5, 0x400, v4
	v_sub_u32_e32 v3, v3, v5
	v_lshrrev_b32_e32 v5, 4, v3
	v_bitop3_b32 v5, v5, v3, 32 bitop3:0x6c
	v_ashrrev_i32_e32 v3, 31, v5
	v_lshrrev_b32_e32 v3, 26, v3
	v_add_u32_e32 v6, v5, v3
	v_lshlrev_b32_e32 v7, 3, v4
	v_ashrrev_i32_e32 v3, 6, v6
	v_and_b32_e32 v7, -16, v7
	v_add_u32_e32 v7, v3, v7
	v_and_b32_e32 v3, 3, v3
	v_lshrrev_b32_e32 v8, 2, v7
	v_lshlrev_b32_e32 v9, 1, v7
	v_and_or_b32 v3, v7, s2, v3
	v_and_b32_e32 v8, 4, v8
	v_and_b32_e32 v9, 24, v9
	v_or3_b32 v3, v3, v8, v9
	v_mul_lo_u32 v8, v3, s1
	v_lshlrev_b32_e32 v3, 5, v4
	v_and_b32_e32 v4, 0xc0, v6
	v_sub_u32_e32 v4, v5, v4
	v_ashrrev_i16_sdwa v4, v234, sext(v4) dst_sel:DWORD dst_unused:UNUSED_PAD src0_sel:DWORD src1_sel:BYTE_0
	v_and_b32_e32 v3, 32, v3
	v_bfe_i32 v4, v4, 0, 16
	v_add_u32_e32 v6, v3, v4
	v_mul_lo_u32 v5, v7, s1
	v_mov_b32_e32 v130, v237
	v_mov_b32_e32 v132, v233
	v_bfe_i32 v6, v2, 27, 1
	v_lshrrev_b32_e32 v6, 22, v6
	v_add_u32_e32 v6, v0, v6
	v_and_b32_e32 v6, 0xfffffc00, v6
	v_sub_u32_e32 v0, v0, v6
	v_lshrrev_b32_e32 v6, 4, v0
	v_ashrrev_i32_e32 v8, 31, v2
	v_bitop3_b32 v0, v6, v0, 32 bitop3:0x6c
	v_lshrrev_b32_e32 v8, 26, v8
	v_ashrrev_i32_e32 v6, 31, v0
	v_add_u32_e32 v8, v2, v8
	s_lshl_b32 s30, s1, 8
	v_lshrrev_b32_e32 v6, 26, v6
	v_ashrrev_i32_e32 v8, 6, v8
	s_lshl_b64 s[78:79], s[30:31], 1
	v_add_u32_e32 v7, v0, v6
	v_lshlrev_b32_e32 v9, 3, v8
	v_ashrrev_i32_e32 v6, 6, v7
	v_and_b32_e32 v9, -16, v9
	s_mul_i32 s4, s78, s33
	s_mul_hi_u32 s6, s78, s93
	v_add_u32_e32 v9, v6, v9
	s_add_i32 s4, s6, s4
	s_bfe_u32 s6, s1, 0x10017
	v_and_b32_e32 v6, 3, v6
	v_lshrrev_b32_e32 v10, 2, v9
	v_lshlrev_b32_e32 v11, 1, v9
	s_mul_i32 s7, s6, s93
	v_and_or_b32 v6, v9, s2, v6
	v_and_b32_e32 v10, 4, v10
	v_and_b32_e32 v11, 24, v11
	v_and_b32_e32 v7, 0xc0, v7
	s_add_i32 s4, s4, s7
	s_mul_i32 s7, s78, s47
	s_mul_hi_u32 s23, s78, s46
	s_ashr_i32 s9, s8, 6
	v_or3_b32 v6, v6, v10, v11
	v_sub_u32_e32 v0, v0, v7
	s_add_i32 s7, s23, s7
	s_mul_i32 s6, s6, s46
	s_ashr_i32 s18, s8, 8
	s_lshl_b32 s82, s9, 10
	v_mul_lo_u32 v10, v6, s1
	v_lshlrev_b32_e32 v6, 5, v8
	v_ashrrev_i16_sdwa v0, v234, sext(v0) dst_sel:DWORD dst_unused:UNUSED_PAD src0_sel:DWORD src1_sel:BYTE_0
	s_add_i32 s7, s7, s6
	s_mul_i32 s6, s78, s46
	v_and_b32_e32 v6, 32, v6
	v_bfe_i32 v7, v0, 0, 16
	s_add_u32 s72, s70, s6
	v_add_u32_e32 v11, v6, v7
	s_addc_u32 s73, s71, s7
	s_add_i32 s83, s82, 0
	v_mov_b32_e32 v0, v236
	s_add_i32 m0, s83, 0x10000
	s_mul_i32 s19, s78, s93
	global_load_lds_dwordx4 v0, s[72:73]
	s_add_i32 m0, s83, 0x12000
	s_add_u32 s6, s72, s30
	global_load_lds_dwordx4 v130, s[72:73]
	s_addc_u32 s7, s73, 0
	s_add_i32 m0, s83, 0x14000
	v_mul_lo_u32 v8, v9, s1
	global_load_lds_dwordx4 v0, s[6:7]
	s_add_i32 m0, s83, 0x16000
	s_add_u32 s74, s68, s19
	s_addc_u32 s75, s69, s4
	s_add_i32 s23, s83, 0x2000
	v_mov_b32_e32 v134, v232
	global_load_lds_dwordx4 v130, s[6:7]
	s_mov_b32 m0, s83
	s_add_u32 s80, s74, s30
	global_load_lds_dwordx4 v134, s[74:75]
	s_mov_b32 m0, s23
	s_addc_u32 s81, s75, 0
	s_add_i32 s4, s83, 0x4000
	global_load_lds_dwordx4 v132, s[74:75]
	s_mov_b32 m0, s4
	s_add_i32 s55, s83, 0x6000
	global_load_lds_dwordx4 v134, s[80:81]
	s_mov_b32 m0, s55
	s_cmp_eq_u32 s18, 1
	global_load_lds_dwordx4 v132, s[80:81]
	s_cselect_b64 s[80:81], -1, 0
	s_cmp_lg_u32 s18, 1
	s_cbranch_scc1 .LBB0_46
	s_barrier
.LBB0_46:
	v_lshl_add_u64 v[10:11], s[72:73], 0, v[0:1]
	v_mov_b32_e32 v131, v1
	v_lshl_add_u64 v[12:13], s[72:73], 0, v[130:131]
	v_mov_b32_e32 v135, v1
	s_add_i32 m0, s83, 0x18000
	v_lshl_add_u64 v[10:11], v[10:11], 0, s[40:41]
	s_waitcnt vmcnt(0)
	v_lshl_add_u64 v[18:19], s[74:75], 0, v[134:135]
	v_mov_b32_e32 v133, v1
	s_waitcnt vmcnt(2)
	s_barrier
	global_load_lds_dwordx4 v[10:11], off
	v_lshl_add_u64 v[10:11], v[12:13], 0, s[40:41]
	s_add_i32 m0, s83, 0x1a000
	s_add_i32 s19, s83, 0x8000
	v_lshl_add_u64 v[20:21], s[74:75], 0, v[132:133]
	global_load_lds_dwordx4 v[10:11], off
	v_lshl_add_u64 v[10:11], v[18:19], 0, s[40:41]
	s_mov_b32 m0, s19
	s_add_i32 s51, s83, 0xa000
	v_lshl_add_u64 v[14:15], s[6:7], 0, v[0:1]
	global_load_lds_dwordx4 v[10:11], off
	v_lshl_add_u64 v[10:11], v[20:21], 0, s[40:41]
	s_mov_b32 m0, s51
	v_lshl_add_u64 v[16:17], s[6:7], 0, v[130:131]
	global_load_lds_dwordx4 v[10:11], off
	s_add_i32 m0, s83, 0x1c000
	v_lshl_add_u64 v[10:11], v[14:15], 0, s[40:41]
	global_load_lds_dwordx4 v[10:11], off
	v_lshl_add_u64 v[10:11], v[16:17], 0, s[40:41]
	s_add_i32 m0, s83, 0x1e000
	v_and_b32_e32 v9, 15, v2
	global_load_lds_dwordx4 v[10:11], off
	v_lshrrev_b32_e32 v10, 1, v2
	v_and_b32_e32 v10, 24, v10
	v_lshlrev_b32_e32 v11, 1, v10
	v_lshlrev_b32_e32 v2, 2, v2
	s_lshr_b32 s88, s1, 6
	v_lshl_or_b32 v142, s18, 6, v9
	v_lshl_or_b32 v9, v9, 6, v11
	s_lshl_b32 s1, s18, 13
	v_and_b32_e32 v2, 32, v2
	v_bitop3_b32 v11, v9, s1, v2 bitop3:0xde
	s_lshl_b32 s1, s9, 5
	s_and_b32 s1, s1, 0x60
	s_lshl_b32 s6, s1, 7
	v_mov_b32_e32 v143, v252
	v_add_u32_e32 v2, v8, v6
	s_waitcnt vmcnt(6)
	s_add_i32 s18, s88, -2
	v_add_lshl_u32 v6, v2, v7, 1
	v_add_u32_e32 v2, v5, v3
	s_cmpk_lt_u32 s8, 0x100
	v_mov_b32_e32 v7, v1
	v_add_lshl_u32 v2, v2, v4, 1
	v_mov_b32_e32 v3, v1
	s_cselect_b64 s[94:95], -1, 0
	v_or_b32_e32 v144, s1, v10
	v_lshl_add_u64 v[136:137], s[30:31], 0, v[134:135]
	v_lshl_add_u64 v[138:139], s[30:31], 0, v[132:133]
	s_mov_b32 s84, 0
	v_mov_b32_e32 v145, v227
	s_mov_b32 s85, s3
	s_mov_b32 s87, s93
	s_barrier
	s_branch .LBB0_49

; #define PG8_STAGE(bufoff, gbase, voff) do { _Pragma("unroll") for (int _i = 0; _i < 2; ++_i) \
;         __builtin_amdgcn_global_load_lds((const unsigned*)((const char*)(gbase) + (voff)[_i]), (PG8_LAS unsigned*)(lds + (bufoff) + ldsw + _i * 8192), 16, 0, 0); } while (0)
; #define PG8_LDA(dst, b, h) do { _Pragma("unroll") for (int m = 0; m < 4; ++m) _Pragma("unroll") for (int k = 0; k < 2; ++k) dst[m][k] = *(const PG8_LAS bf16x8*)(lds + PG8_SA(b, h) + aoff + m * 2048 + k * 1024); } while (0)
; #define PG8_LDB(dst, b, h) do { _Pragma("unroll") for (int n = 0; n < 2; ++n) _Pragma("unroll") for (int k = 0; k < 2; ++k) dst[n][k] = *(const PG8_LAS bf16x8*)(lds + PG8_SB(b, h) + boff + n * 2048 + k * 1024); } while (0)
; #define PG8_MMA(ai, bj, At, Bt) do { __builtin_amdgcn_s_setprio(1); _Pragma("unroll") for (int m = 0; m < 4; ++m) _Pragma("unroll") for (int n = 0; n < 2; ++n) _Pragma("unroll") for (int k = 0; k < 2; ++k) \
;         acc[ai][bj][m][n] = __builtin_amdgcn_mfma_f32_16x16x32_bf16(Bt[n][k], At[m][k], acc[ai][bj][m][n], 0, 0, 0); __builtin_amdgcn_s_setprio(0); } while (0)
; #define PG8_WAIT_V(n) asm volatile("s_waitcnt vmcnt(" #n ")" ::: "memory")
; #define PG8_WAIT_L(n) asm volatile("s_waitcnt lgkmcnt(" #n ")" ::: "memory")
; #define PG8_BAR __builtin_amdgcn_s_barrier()
; template <class Epi, class Sched, bool ALIGN_EPI = false, bool SP2 = false>
; __device__ __forceinline__ void gemm_phase(PG8_LAS unsigned char* lds, const Gemm g, const Sched& S, const Epi& E) {
;     ...
;             const char* a1 = cA + (size_t)(t + 1) * kstep;
;             const char* a2 = last ? nA : cA + (size_t)(t + 2) * kstep; const char* b2 = last ? nB : cB + (size_t)(t + 2) * kstep;
;             const char* a3 = a2 + kstep; const char* b3 = b2 + kstep;
;             if (last && has_next) S.a_ready(nxt);
;             if constexpr (SP2) {
;             PG8_LDB(B0, 0, 0); PG8_LDB(B1, 0, 1); PG8_SCHED; PG8_LDA(At, 0, 0); PG8_STAGE(PG8_SA(1, 1), a1 + hstep, voffA);
;             PG8_WAIT_V(8); PG8_WAIT_L(0); PG8_BAR; PG8_MMA(0, 0, At, B0); PG8_MMA(0, 1, At, B1); PG8_BAR; PG8_SCHED;
;             PG8_LDA(At, 0, 1); PG8_STAGE(PG8_SB(0, 0), b2, voffB); PG8_STAGE(PG8_SB(0, 1), b2 + hstep, voffB); PG8_STAGE(PG8_SA(0, 0), a2, voffA);
;             PG8_WAIT_V(8); PG8_WAIT_L(0); PG8_BAR; PG8_MMA(1, 0, At, B0); PG8_MMA(1, 1, At, B1); PG8_BAR; PG8_SCHED;
.LBB0_60:
	s_add_i32 s1, s72, 2
	s_add_u32 s90, vcc_lo, 0x80
	s_addc_u32 s73, vcc_hi, 0
	s_add_i32 s29, 0, 0x10000
	s_cmp_eq_u32 s18, s72
	s_cselect_b32 s73, s9, s73
	s_cselect_b32 s72, s8, s90
	v_add_u32_e32 v140, s29, v143
	v_add_u32_e32 v250, s29, v226
	s_cselect_b32 s91, s97, s75
	s_cselect_b32 s90, s96, s74
	s_add_i32 s22, 0, 0x14000
	ds_read_b128 v[146:149], v140
	ds_read_b128 v[150:153], v250
	ds_read_b128 v[154:157], v140 offset:2048
	ds_read_b128 v[158:161], v250 offset:2048
	v_add_u32_e32 v140, s22, v143
	v_add_u32_e32 v251, s22, v226
	ds_read_b128 v[162:165], v140
	ds_read_b128 v[166:169], v251
	ds_read_b128 v[170:173], v140 offset:2048
	ds_read_b128 v[174:177], v251 offset:2048
	v_lshl_add_u64 v[140:141], vcc, 0, v[136:137]
	s_add_i32 m0, s83, 0xc000
	ds_read_b128 v[178:181], v145
	ds_read_b128 v[182:185], v225
	ds_read_b128 v[186:189], v145 offset:2048
	ds_read_b128 v[190:193], v225 offset:2048
	ds_read_b128 v[194:197], v145 offset:4096
	ds_read_b128 v[198:201], v225 offset:4096
	ds_read_b128 v[202:205], v145 offset:6144
	ds_read_b128 v[206:209], v225 offset:6144
	global_load_lds_dwordx4 v[140:141], off
	v_lshl_add_u64 v[140:141], vcc, 0, v[138:139]
	s_add_i32 m0, s83, 0xe000
	s_nop 0
	global_load_lds_dwordx4 v[140:141], off
	s_waitcnt vmcnt(8)
	s_waitcnt lgkmcnt(0)
	s_barrier
	s_setprio 1
	s_waitcnt lgkmcnt(0)
	v_mfma_f32_16x16x32_bf16 v[126:129], v[146:149], v[178:181], v[126:129]
	v_mfma_f32_16x16x32_bf16 v[122:125], v[154:157], v[178:181], v[122:125]
	v_mfma_f32_16x16x32_bf16 v[118:121], v[146:149], v[186:189], v[118:121]
	v_mfma_f32_16x16x32_bf16 v[110:113], v[154:157], v[186:189], v[110:113]
	v_mfma_f32_16x16x32_bf16 v[102:105], v[146:149], v[194:197], v[102:105]
	v_mfma_f32_16x16x32_bf16 v[94:97], v[154:157], v[194:197], v[94:97]
	v_mfma_f32_16x16x32_bf16 v[86:89], v[146:149], v[202:205], v[86:89]
	v_mfma_f32_16x16x32_bf16 v[78:81], v[154:157], v[202:205], v[78:81]
	v_mfma_f32_16x16x32_bf16 v[126:129], v[150:153], v[182:185], v[126:129]
	v_mfma_f32_16x16x32_bf16 v[122:125], v[158:161], v[182:185], v[122:125]
	v_mfma_f32_16x16x32_bf16 v[118:121], v[150:153], v[190:193], v[118:121]
	v_mfma_f32_16x16x32_bf16 v[110:113], v[158:161], v[190:193], v[110:113]
	v_mfma_f32_16x16x32_bf16 v[102:105], v[150:153], v[198:201], v[102:105]
	v_mfma_f32_16x16x32_bf16 v[94:97], v[158:161], v[198:201], v[94:97]
	v_mfma_f32_16x16x32_bf16 v[86:89], v[150:153], v[206:209], v[86:89]
	v_mfma_f32_16x16x32_bf16 v[78:81], v[158:161], v[206:209], v[78:81]
	s_setprio 0
	s_setprio 1
	v_mfma_f32_16x16x32_bf16 v[114:117], v[162:165], v[178:181], v[114:117]
	v_mfma_f32_16x16x32_bf16 v[106:109], v[170:173], v[178:181], v[106:109]
	v_mfma_f32_16x16x32_bf16 v[98:101], v[162:165], v[186:189], v[98:101]
	v_mfma_f32_16x16x32_bf16 v[90:93], v[170:173], v[186:189], v[90:93]
	v_mfma_f32_16x16x32_bf16 v[82:85], v[162:165], v[194:197], v[82:85]
	v_mfma_f32_16x16x32_bf16 v[74:77], v[170:173], v[194:197], v[74:77]
	v_mfma_f32_16x16x32_bf16 v[70:73], v[162:165], v[202:205], v[70:73]
	v_mfma_f32_16x16x32_bf16 v[66:69], v[170:173], v[202:205], v[66:69]
	v_mfma_f32_16x16x32_bf16 v[114:117], v[166:169], v[182:185], v[114:117]
	v_mfma_f32_16x16x32_bf16 v[106:109], v[174:177], v[182:185], v[106:109]
	v_mfma_f32_16x16x32_bf16 v[98:101], v[166:169], v[190:193], v[98:101]
	v_mfma_f32_16x16x32_bf16 v[90:93], v[174:177], v[190:193], v[90:93]
	v_mfma_f32_16x16x32_bf16 v[82:85], v[166:169], v[198:201], v[82:85]
	v_mfma_f32_16x16x32_bf16 v[74:77], v[174:177], v[198:201], v[74:77]
	v_mfma_f32_16x16x32_bf16 v[70:73], v[166:169], v[206:209], v[70:73]
	v_mfma_f32_16x16x32_bf16 v[66:69], v[174:177], v[206:209], v[66:69]
	s_setprio 0
	s_barrier
	s_add_i32 s29, s29, s82
	v_lshl_add_u64 v[140:141], s[90:91], 0, v[0:1]
	s_mov_b32 m0, s29
	ds_read_b128 v[178:181], v145 offset:16384
	ds_read_b128 v[182:185], v225 offset:16384
	ds_read_b128 v[186:189], v145 offset:18432
	ds_read_b128 v[190:193], v225 offset:18432
	ds_read_b128 v[194:197], v145 offset:20480
	ds_read_b128 v[198:201], v225 offset:20480
	ds_read_b128 v[202:205], v145 offset:22528
	ds_read_b128 v[206:209], v225 offset:22528
	global_load_lds_dwordx4 v[140:141], off
	s_add_i32 m0, s29, 0x2000
	v_lshl_add_u64 v[210:211], s[90:91], 0, v[130:131]
	s_add_u32 s90, s90, s30
	s_addc_u32 s91, s91, 0
	s_add_i32 s22, s22, s82
	global_load_lds_dwordx4 v[210:211], off
	v_lshl_add_u64 v[212:213], s[90:91], 0, v[0:1]
	s_mov_b32 m0, s22
	v_lshl_add_u64 v[214:215], s[90:91], 0, v[130:131]
	global_load_lds_dwordx4 v[212:213], off
	s_add_i32 m0, s22, 0x2000
	v_lshl_add_u64 v[216:217], s[72:73], 0, v[134:135]
	global_load_lds_dwordx4 v[214:215], off
	s_mov_b32 m0, s83
	v_lshl_add_u64 v[218:219], s[72:73], 0, v[132:133]
	global_load_lds_dwordx4 v[216:217], off
	s_mov_b32 m0, s23
	s_nop 0
	global_load_lds_dwordx4 v[218:219], off
	s_waitcnt vmcnt(8)
	s_waitcnt lgkmcnt(0)
	s_barrier
; #define PG8_STAGE(bufoff, gbase, voff) do { _Pragma("unroll") for (int _i = 0; _i < 2; ++_i) \
;         __builtin_amdgcn_global_load_lds((const unsigned*)((const char*)(gbase) + (voff)[_i]), (PG8_LAS unsigned*)(lds + (bufoff) + ldsw + _i * 8192), 16, 0, 0); } while (0)
; #define PG8_LDA(dst, b, h) do { _Pragma("unroll") for (int m = 0; m < 4; ++m) _Pragma("unroll") for (int k = 0; k < 2; ++k) dst[m][k] = *(const PG8_LAS bf16x8*)(lds + PG8_SA(b, h) + aoff + m * 2048 + k * 1024); } while (0)
; #define PG8_LDB(dst, b, h) do { _Pragma("unroll") for (int n = 0; n < 2; ++n) _Pragma("unroll") for (int k = 0; k < 2; ++k) dst[n][k] = *(const PG8_LAS bf16x8*)(lds + PG8_SB(b, h) + boff + n * 2048 + k * 1024); } while (0)
; #define PG8_MMA(ai, bj, At, Bt) do { __builtin_amdgcn_s_setprio(1); _Pragma("unroll") for (int m = 0; m < 4; ++m) _Pragma("unroll") for (int n = 0; n < 2; ++n) _Pragma("unroll") for (int k = 0; k < 2; ++k) \
;         acc[ai][bj][m][n] = __builtin_amdgcn_mfma_f32_16x16x32_bf16(Bt[n][k], At[m][k], acc[ai][bj][m][n], 0, 0, 0); __builtin_amdgcn_s_setprio(0); } while (0)
; #define PG8_WAIT_V(n) asm volatile("s_waitcnt vmcnt(" #n ")" ::: "memory")
; #define PG8_WAIT_L(n) asm volatile("s_waitcnt lgkmcnt(" #n ")" ::: "memory")
; #define PG8_BAR __builtin_amdgcn_s_barrier()
; #define PG8_SCHED __builtin_amdgcn_sched_barrier(0)
; template <class Epi, class Sched, bool ALIGN_EPI = false, bool SP2 = false>
; __device__ __forceinline__ void gemm_phase(PG8_LAS unsigned char* lds, const Gemm g, const Sched& S, const Epi& E) {
;     ...
;             PG8_WAIT_V(8); PG8_WAIT_L(0); PG8_BAR; PG8_MMA(1, 0, At, B0); PG8_MMA(1, 1, At, B1); PG8_BAR; PG8_SCHED;
;             PG8_LDB(B0, 1, 0); PG8_LDB(B1, 1, 1); PG8_SCHED; PG8_LDA(At, 1, 0); PG8_STAGE(PG8_SA(0, 1), a2 + hstep, voffA);
;             PG8_WAIT_V(8); PG8_WAIT_L(0); PG8_BAR; PG8_MMA(0, 0, At, B0); PG8_MMA(0, 1, At, B1); PG8_BAR; PG8_SCHED;
	s_setprio 1
	s_waitcnt lgkmcnt(0)
	v_mfma_f32_16x16x32_bf16 v[62:65], v[146:149], v[178:181], v[62:65]
	v_mfma_f32_16x16x32_bf16 v[58:61], v[154:157], v[178:181], v[58:61]
	v_mfma_f32_16x16x32_bf16 v[54:57], v[146:149], v[186:189], v[54:57]
	v_mfma_f32_16x16x32_bf16 v[46:49], v[154:157], v[186:189], v[46:49]
	v_mfma_f32_16x16x32_bf16 v[38:41], v[146:149], v[194:197], v[38:41]
	v_mfma_f32_16x16x32_bf16 v[30:33], v[154:157], v[194:197], v[30:33]
	v_mfma_f32_16x16x32_bf16 v[22:25], v[146:149], v[202:205], v[22:25]
	v_mfma_f32_16x16x32_bf16 v[14:17], v[154:157], v[202:205], v[14:17]
	v_mfma_f32_16x16x32_bf16 v[62:65], v[150:153], v[182:185], v[62:65]
	v_mfma_f32_16x16x32_bf16 v[58:61], v[158:161], v[182:185], v[58:61]
	v_mfma_f32_16x16x32_bf16 v[54:57], v[150:153], v[190:193], v[54:57]
	v_mfma_f32_16x16x32_bf16 v[46:49], v[158:161], v[190:193], v[46:49]
	v_mfma_f32_16x16x32_bf16 v[38:41], v[150:153], v[198:201], v[38:41]
	v_mfma_f32_16x16x32_bf16 v[30:33], v[158:161], v[198:201], v[30:33]
	v_mfma_f32_16x16x32_bf16 v[22:25], v[150:153], v[206:209], v[22:25]
	v_mfma_f32_16x16x32_bf16 v[14:17], v[158:161], v[206:209], v[14:17]
	s_setprio 0
	s_setprio 1
	v_mfma_f32_16x16x32_bf16 v[50:53], v[162:165], v[178:181], v[50:53]
	v_mfma_f32_16x16x32_bf16 v[42:45], v[170:173], v[178:181], v[42:45]
	v_mfma_f32_16x16x32_bf16 v[34:37], v[162:165], v[186:189], v[34:37]
	v_mfma_f32_16x16x32_bf16 v[26:29], v[170:173], v[186:189], v[26:29]
	v_mfma_f32_16x16x32_bf16 v[18:21], v[162:165], v[194:197], v[18:21]
	v_mfma_f32_16x16x32_bf16 v[10:13], v[170:173], v[194:197], v[10:13]
	v_mfma_f32_16x16x32_bf16 v[6:9], v[162:165], v[202:205], v[6:9]
	v_mfma_f32_16x16x32_bf16 v[2:5], v[170:173], v[202:205], v[2:5]
	v_mfma_f32_16x16x32_bf16 v[50:53], v[166:169], v[182:185], v[50:53]
	v_mfma_f32_16x16x32_bf16 v[42:45], v[174:177], v[182:185], v[42:45]
	v_mfma_f32_16x16x32_bf16 v[34:37], v[166:169], v[190:193], v[34:37]
	v_mfma_f32_16x16x32_bf16 v[26:29], v[174:177], v[190:193], v[26:29]
	v_mfma_f32_16x16x32_bf16 v[18:21], v[166:169], v[198:201], v[18:21]
	v_mfma_f32_16x16x32_bf16 v[10:13], v[174:177], v[198:201], v[10:13]
	v_mfma_f32_16x16x32_bf16 v[6:9], v[166:169], v[206:209], v[6:9]
	v_mfma_f32_16x16x32_bf16 v[2:5], v[174:177], v[206:209], v[2:5]
	s_setprio 0
	s_barrier
	s_add_i32 s22, 0, 0x18000
	s_add_i32 s29, 0, 0x1c000
	v_add_u32_e32 v158, s22, v143
	v_add_u32_e32 v250, s22, v226
	v_add_u32_e32 v174, s29, v143
	v_add_u32_e32 v251, s29, v226
	ds_read_b128 v[146:149], v158
	ds_read_b128 v[150:153], v250
	ds_read_b128 v[154:157], v158 offset:2048
	ds_read_b128 v[158:161], v250 offset:2048
	ds_read_b128 v[162:165], v174
	ds_read_b128 v[166:169], v251
	ds_read_b128 v[170:173], v174 offset:2048
	ds_read_b128 v[174:177], v251 offset:2048
	s_add_u32 s72, s72, s30
	s_addc_u32 s73, s73, 0
	s_mov_b32 m0, s4
	v_lshl_add_u64 v[220:221], s[72:73], 0, v[134:135]
	ds_read_b128 v[178:181], v145 offset:32768
	ds_read_b128 v[182:185], v225 offset:32768
	ds_read_b128 v[186:189], v145 offset:34816
	ds_read_b128 v[190:193], v225 offset:34816
	ds_read_b128 v[194:197], v145 offset:36864
	ds_read_b128 v[198:201], v225 offset:36864
	ds_read_b128 v[202:205], v145 offset:38912
	ds_read_b128 v[206:209], v225 offset:38912
	global_load_lds_dwordx4 v[220:221], off
	v_lshl_add_u64 v[220:221], s[72:73], 0, v[132:133]
	s_mov_b32 m0, s55
	s_nop 0
	global_load_lds_dwordx4 v[220:221], off
	s_waitcnt vmcnt(8)
	s_waitcnt lgkmcnt(0)
	s_barrier
	s_setprio 1
	s_waitcnt lgkmcnt(0)
	v_mfma_f32_16x16x32_bf16 v[126:129], v[146:149], v[178:181], v[126:129]
	v_mfma_f32_16x16x32_bf16 v[122:125], v[154:157], v[178:181], v[122:125]
	v_mfma_f32_16x16x32_bf16 v[118:121], v[146:149], v[186:189], v[118:121]
	v_mfma_f32_16x16x32_bf16 v[110:113], v[154:157], v[186:189], v[110:113]
	v_mfma_f32_16x16x32_bf16 v[102:105], v[146:149], v[194:197], v[102:105]
	v_mfma_f32_16x16x32_bf16 v[94:97], v[154:157], v[194:197], v[94:97]
	v_mfma_f32_16x16x32_bf16 v[86:89], v[146:149], v[202:205], v[86:89]
	v_mfma_f32_16x16x32_bf16 v[78:81], v[154:157], v[202:205], v[78:81]
	v_mfma_f32_16x16x32_bf16 v[126:129], v[150:153], v[182:185], v[126:129]
	v_mfma_f32_16x16x32_bf16 v[122:125], v[158:161], v[182:185], v[122:125]
	v_mfma_f32_16x16x32_bf16 v[118:121], v[150:153], v[190:193], v[118:121]
	v_mfma_f32_16x16x32_bf16 v[110:113], v[158:161], v[190:193], v[110:113]
	v_mfma_f32_16x16x32_bf16 v[102:105], v[150:153], v[198:201], v[102:105]
	v_mfma_f32_16x16x32_bf16 v[94:97], v[158:161], v[198:201], v[94:97]
	v_mfma_f32_16x16x32_bf16 v[86:89], v[150:153], v[206:209], v[86:89]
	v_mfma_f32_16x16x32_bf16 v[78:81], v[158:161], v[206:209], v[78:81]
	s_setprio 0
	s_setprio 1
	v_mfma_f32_16x16x32_bf16 v[114:117], v[162:165], v[178:181], v[114:117]
	v_mfma_f32_16x16x32_bf16 v[106:109], v[170:173], v[178:181], v[106:109]
	v_mfma_f32_16x16x32_bf16 v[98:101], v[162:165], v[186:189], v[98:101]
	v_mfma_f32_16x16x32_bf16 v[90:93], v[170:173], v[186:189], v[90:93]
	v_mfma_f32_16x16x32_bf16 v[82:85], v[162:165], v[194:197], v[82:85]
	v_mfma_f32_16x16x32_bf16 v[74:77], v[170:173], v[194:197], v[74:77]
	v_mfma_f32_16x16x32_bf16 v[70:73], v[162:165], v[202:205], v[70:73]
	v_mfma_f32_16x16x32_bf16 v[66:69], v[170:173], v[202:205], v[66:69]
	v_mfma_f32_16x16x32_bf16 v[114:117], v[166:169], v[182:185], v[114:117]
	v_mfma_f32_16x16x32_bf16 v[106:109], v[174:177], v[182:185], v[106:109]
	v_mfma_f32_16x16x32_bf16 v[98:101], v[166:169], v[190:193], v[98:101]
	v_mfma_f32_16x16x32_bf16 v[90:93], v[174:177], v[190:193], v[90:93]
	v_mfma_f32_16x16x32_bf16 v[82:85], v[166:169], v[198:201], v[82:85]
	v_mfma_f32_16x16x32_bf16 v[74:77], v[174:177], v[198:201], v[74:77]
	v_mfma_f32_16x16x32_bf16 v[70:73], v[166:169], v[206:209], v[70:73]
	v_mfma_f32_16x16x32_bf16 v[66:69], v[174:177], v[206:209], v[66:69]
	s_setprio 0
	s_barrier
; #define PG8_STAGE(bufoff, gbase, voff) do { _Pragma("unroll") for (int _i = 0; _i < 2; ++_i) \
;         __builtin_amdgcn_global_load_lds((const unsigned*)((const char*)(gbase) + (voff)[_i]), (PG8_LAS unsigned*)(lds + (bufoff) + ldsw + _i * 8192), 16, 0, 0); } while (0)
; #define PG8_LDA(dst, b, h) do { _Pragma("unroll") for (int m = 0; m < 4; ++m) _Pragma("unroll") for (int k = 0; k < 2; ++k) dst[m][k] = *(const PG8_LAS bf16x8*)(lds + PG8_SA(b, h) + aoff + m * 2048 + k * 1024); } while (0)
; #define PG8_MMA(ai, bj, At, Bt) do { __builtin_amdgcn_s_setprio(1); _Pragma("unroll") for (int m = 0; m < 4; ++m) _Pragma("unroll") for (int n = 0; n < 2; ++n) _Pragma("unroll") for (int k = 0; k < 2; ++k) \
;         acc[ai][bj][m][n] = __builtin_amdgcn_mfma_f32_16x16x32_bf16(Bt[n][k], At[m][k], acc[ai][bj][m][n], 0, 0, 0); __builtin_amdgcn_s_setprio(0); } while (0)
; #define PG8_WAIT_V(n) asm volatile("s_waitcnt vmcnt(" #n ")" ::: "memory")
; #define PG8_WAIT_L(n) asm volatile("s_waitcnt lgkmcnt(" #n ")" ::: "memory")
; #define PG8_BAR __builtin_amdgcn_s_barrier()
; #define PG8_SCHED __builtin_amdgcn_sched_barrier(0)
; template <class Epi, class Sched, bool ALIGN_EPI = false, bool SP2 = false>
; __device__ __forceinline__ void gemm_phase(PG8_LAS unsigned char* lds, const Gemm g, const Sched& S, const Epi& E) {
;     ...
;             PG8_LDA(At, 1, 1); PG8_STAGE(PG8_SB(1, 0), b3, voffB); PG8_STAGE(PG8_SB(1, 1), b3 + hstep, voffB); PG8_STAGE(PG8_SA(1, 0), a3, voffA);
;             PG8_WAIT_V(8); PG8_WAIT_L(0); PG8_BAR; PG8_MMA(1, 0, At, B0); PG8_MMA(1, 1, At, B1); PG8_BAR; PG8_SCHED;
	s_add_i32 s22, s22, s82
	v_lshl_add_u64 v[140:141], v[140:141], 0, s[40:41]
	s_mov_b32 m0, s22
	ds_read_b128 v[178:181], v145 offset:49152
	ds_read_b128 v[182:185], v225 offset:49152
	ds_read_b128 v[186:189], v145 offset:51200
	ds_read_b128 v[190:193], v225 offset:51200
	ds_read_b128 v[194:197], v145 offset:53248
	ds_read_b128 v[198:201], v225 offset:53248
	ds_read_b128 v[202:205], v145 offset:55296
	ds_read_b128 v[206:209], v225 offset:55296
	global_load_lds_dwordx4 v[140:141], off
	v_lshl_add_u64 v[140:141], v[210:211], 0, s[40:41]
	s_add_i32 m0, s22, 0x2000
	s_add_i32 s22, s29, s82
	global_load_lds_dwordx4 v[140:141], off
	v_lshl_add_u64 v[140:141], v[212:213], 0, s[40:41]
	s_mov_b32 m0, s22
	s_nop 0
	global_load_lds_dwordx4 v[140:141], off
	v_lshl_add_u64 v[140:141], v[214:215], 0, s[40:41]
	s_add_i32 m0, s22, 0x2000
	s_nop 0
	global_load_lds_dwordx4 v[140:141], off
	v_lshl_add_u64 v[140:141], v[216:217], 0, s[40:41]
	s_mov_b32 m0, s19
	s_nop 0
	global_load_lds_dwordx4 v[140:141], off
	v_lshl_add_u64 v[140:141], v[218:219], 0, s[40:41]
	s_mov_b32 m0, s51
	s_nop 0
	global_load_lds_dwordx4 v[140:141], off
	s_waitcnt vmcnt(8)
	s_waitcnt lgkmcnt(0)
	s_barrier
	s_setprio 1
	s_waitcnt lgkmcnt(0)
	v_mfma_f32_16x16x32_bf16 v[62:65], v[146:149], v[178:181], v[62:65]
	v_mfma_f32_16x16x32_bf16 v[58:61], v[154:157], v[178:181], v[58:61]
	v_mfma_f32_16x16x32_bf16 v[54:57], v[146:149], v[186:189], v[54:57]
	v_mfma_f32_16x16x32_bf16 v[46:49], v[154:157], v[186:189], v[46:49]
	v_mfma_f32_16x16x32_bf16 v[38:41], v[146:149], v[194:197], v[38:41]
	v_mfma_f32_16x16x32_bf16 v[30:33], v[154:157], v[194:197], v[30:33]
	v_mfma_f32_16x16x32_bf16 v[22:25], v[146:149], v[202:205], v[22:25]
	v_mfma_f32_16x16x32_bf16 v[14:17], v[154:157], v[202:205], v[14:17]
	v_mfma_f32_16x16x32_bf16 v[62:65], v[150:153], v[182:185], v[62:65]
	v_mfma_f32_16x16x32_bf16 v[58:61], v[158:161], v[182:185], v[58:61]
	v_mfma_f32_16x16x32_bf16 v[54:57], v[150:153], v[190:193], v[54:57]
	v_mfma_f32_16x16x32_bf16 v[46:49], v[158:161], v[190:193], v[46:49]
	v_mfma_f32_16x16x32_bf16 v[38:41], v[150:153], v[198:201], v[38:41]
	v_mfma_f32_16x16x32_bf16 v[30:33], v[158:161], v[198:201], v[30:33]
	v_mfma_f32_16x16x32_bf16 v[22:25], v[150:153], v[206:209], v[22:25]
	v_mfma_f32_16x16x32_bf16 v[14:17], v[158:161], v[206:209], v[14:17]
	s_setprio 0
	s_setprio 1
	v_mfma_f32_16x16x32_bf16 v[50:53], v[162:165], v[178:181], v[50:53]
	v_mfma_f32_16x16x32_bf16 v[42:45], v[170:173], v[178:181], v[42:45]
	v_mfma_f32_16x16x32_bf16 v[34:37], v[162:165], v[186:189], v[34:37]
	v_mfma_f32_16x16x32_bf16 v[26:29], v[170:173], v[186:189], v[26:29]
	v_mfma_f32_16x16x32_bf16 v[18:21], v[162:165], v[194:197], v[18:21]
	v_mfma_f32_16x16x32_bf16 v[10:13], v[170:173], v[194:197], v[10:13]
	v_mfma_f32_16x16x32_bf16 v[6:9], v[162:165], v[202:205], v[6:9]
	v_mfma_f32_16x16x32_bf16 v[2:5], v[170:173], v[202:205], v[2:5]
	v_mfma_f32_16x16x32_bf16 v[50:53], v[166:169], v[182:185], v[50:53]
	v_mfma_f32_16x16x32_bf16 v[42:45], v[174:177], v[182:185], v[42:45]
	v_mfma_f32_16x16x32_bf16 v[34:37], v[166:169], v[190:193], v[34:37]
	v_mfma_f32_16x16x32_bf16 v[26:29], v[174:177], v[190:193], v[26:29]
	v_mfma_f32_16x16x32_bf16 v[18:21], v[166:169], v[198:201], v[18:21]
	v_mfma_f32_16x16x32_bf16 v[10:13], v[174:177], v[198:201], v[10:13]
	v_mfma_f32_16x16x32_bf16 v[6:9], v[166:169], v[206:209], v[6:9]
	v_mfma_f32_16x16x32_bf16 v[2:5], v[174:177], v[206:209], v[2:5]
	s_setprio 0
	s_barrier
	s_add_u32 vcc_lo, vcc_lo, 0x100
	s_addc_u32 vcc_hi, vcc_hi, 0
	s_add_u32 s74, s74, 0x100
	s_addc_u32 s75, s75, 0
	s_cmp_ge_u32 s1, s88
	s_mov_b32 s72, s1
	s_cbranch_scc0 .LBB0_60
	s_and_b64 vcc, exec, s[94:95]
	s_cbranch_vccz .LBB0_63
	s_barrier

; #define LAS __attribute__((address_space(3)))
; __device__ __forceinline__ void row_pass(const RowArgs& R, int gw, int NGW, int lane, LAS unsigned char* lds, int tid) {
;     float gp[2][8], gn[2][8];
; #pragma unroll
;     for (int j = 0; j < 2; ++j)
; #pragma unroll
;         for (int h = 0; h < 2; ++h) {
;             const f32x4 a = R.gpost ? *(const f32x4*)(R.gpost + 8 * lane + 512 * j + 4 * h) : (f32x4){0.f, 0.f, 0.f, 0.f};
;             const f32x4 b = R.gnext ? *(const f32x4*)(R.gnext + 8 * lane + 512 * j + 4 * h) : (f32x4){0.f, 0.f, 0.f, 0.f};
; #pragma unroll
;             for (int e = 0; e < 4; ++e) { gp[j][4 * h + e] = a[e]; gn[j][4 * h + e] = b[e]; }
;         }
;     const f32x4 bf = R.AF ? *(const f32x4*)R.bforget : (f32x4){0.f, 0.f, 0.f, 0.f};
;     const LAS f32x4* afl = (const LAS f32x4*)lds;
;     if (R.AF) {
;         for (int col = tid; col < DM; col += NTHREADS) ((LAS f32x4*)lds)[((col >> 9) * 8 + (col & 7)) * 64 + ((col & 511) >> 3)] = *(const f32x4*)(R.AF + (size_t)col * 4);
;         __syncthreads();
;     }
;     RowRaw qa, qb;
;     if (gw < M) row_load(R, gw, lane, qa);
;     for (int m = gw; m < M; m += 2 * NGW) {
.LBB0_247:
	s_mov_b32 s59, 0xf800000
	s_andn2_b64 vcc, exec, s[10:11]
	s_cbranch_vccnz .LBB0_309
	s_waitcnt lgkmcnt(0)
	s_lshl_b32 s30, s3, 3
	s_cmp_lg_u64 s[78:79], 0
	s_cselect_b64 s[34:35], -1, 0
	s_cmp_lg_u64 s[96:97], 0
	s_cselect_b64 s[36:37], -1, 0
	s_cmp_lg_u64 s[80:81], 0
	v_lshlrev_b32_e32 v0, 4, v80
	s_cselect_b64 s[38:39], -1, 0
	s_cmp_lg_u64 s[14:15], 0
	v_mov_b32_e32 v143, v1
	v_add_u32_e32 v30, 0, v0
	v_cmp_eq_u32_e64 s[10:11], 0, v80
	v_lshl_add_u64 v[26:27], s[14:15], 0, v[0:1]
	s_cselect_b64 s[42:43], -1, 0
	v_lshl_add_u64 v[146:147], s[12:13], 0, v[142:143]
	s_mov_b32 s77, s76
	s_lshl_b32 s89, s3, 4
	s_waitcnt vmcnt(0)
	s_branch .LBB0_250

; __device__ __forceinline__ void row_load(const RowArgs& R, int m, int lane, RowRaw& q) {
;     const size_t off = (size_t)m * DM + 8 * lane;
;     if (R.hin32) {
; #pragma unroll
;         for (int j = 0; j < 2; ++j) { q.v32[j][0] = __builtin_nontemporal_load((const f32x4*)(R.hin32 + off + 512 * j)); q.v32[j][1] = __builtin_nontemporal_load((const f32x4*)(R.hin32 + off + 512 * j + 4)); }
;     } else {
; #pragma unroll
;         for (int j = 0; j < 2; ++j) q.v16[j] = __builtin_nontemporal_load((const u32x4*)(R.hin16 + off + 512 * j));
;     }
.LBB0_253:
	v_lshl_add_u64 v[84:85], v[148:149], 1, s[46:47]
	global_load_dwordx4 v[80:83], v[84:85], off nt
	s_nop 0
	global_load_dwordx4 v[84:87], v[84:85], off offset:1024 nt
	v_mov_b64_e32 v[134:135], v[114:115]
	v_mov_b64_e32 v[138:139], v[110:111]
	v_mov_b64_e32 v[126:127], v[106:107]
	v_mov_b64_e32 v[130:131], v[102:103]
	v_mov_b64_e32 v[132:133], v[112:113]
	v_mov_b64_e32 v[136:137], v[108:109]
	v_mov_b64_e32 v[124:125], v[104:105]
	v_mov_b64_e32 v[128:129], v[100:101]

; __device__ __forceinline__ void row_load(const RowArgs& R, int m, int lane, RowRaw& q) {
;     ...
;     if (R.F2) {
; #pragma unroll
;         for (int j = 0; j < 2; ++j) q.e[j] = __builtin_nontemporal_load((const u32x4*)(R.F2 + off + 512 * j));
;     }
;     if (R.p) q.p = __builtin_nontemporal_load((const f32x4*)(R.p + (size_t)m * PLE + 4 * lane));
.LBB0_256:
	s_andn2_b64 vcc, exec, s[42:43]
	s_cbranch_vccnz .LBB0_258
	v_lshl_add_u64 v[96:97], v[26:27], 0, s[14:15]
	global_load_dwordx4 v[96:99], v[96:97], off nt
.LBB0_258:
	s_and_b64 vcc, exec, s[12:13]
	s_cbranch_vccnz .Lrp_nowait258
	s_waitcnt vmcnt(0)
.Lrp_nowait258:
	v_mov_b64_e32 v[100:101], v[128:129]
	v_mov_b64_e32 v[104:105], v[124:125]
	v_mov_b64_e32 v[108:109], v[136:137]
	v_mov_b64_e32 v[112:113], v[132:133]
	v_mov_b64_e32 v[102:103], v[130:131]
	v_mov_b64_e32 v[106:107], v[126:127]
	v_mov_b64_e32 v[110:111], v[138:139]
	v_mov_b64_e32 v[114:115], v[134:135]

; __device__ __forceinline__ float hlo(unsigned w) { return (float)__builtin_bit_cast(h16x2, w).x; }
; __device__ __forceinline__ float hhi(unsigned w) { return (float)__builtin_bit_cast(h16x2, w).y; }
; #define UNPK_BF(dst, SRC_) do { const u32x4 t_ = (SRC_); dst[0] = bflo(t_.x); dst[1] = bfhi(t_.x); dst[2] = bflo(t_.y); dst[3] = bfhi(t_.y); dst[4] = bflo(t_.z); dst[5] = bfhi(t_.z); dst[6] = bflo(t_.w); dst[7] = bfhi(t_.w); } while (0)
; __device__ __forceinline__ void row_process(const RowArgs& R, int m, int lane, const RowRaw& q, const float (&gp)[2][8], const float (&gn)[2][8], const f32x4 bf, const LAS f32x4* afl) {
;     ...
;         for (int j = 0; j < 2; ++j) { const u32x4 w = q.v16[j]; v[j][0] = hlo(w.x); v[j][1] = hhi(w.x); v[j][2] = hlo(w.y); v[j][3] = hhi(w.y); v[j][4] = hlo(w.z); v[j][5] = hhi(w.z); v[j][6] = hlo(w.w); v[j][7] = hhi(w.w); }
;     }
;     if (R.F) {
;         float f[2][8];
; #pragma unroll
;         for (int j = 0; j < 2; ++j) UNPK_BF(f[j], q.f[j]);
;         if (R.F2) {
;             float e[2][8]; float ss = 0.f;
; #pragma unroll
;             for (int j = 0; j < 2; ++j) { UNPK_BF(e[j], q.e[j]);
; #pragma unroll
;                 for (int c = 0; c < 8; ++c) ss += e[j][c] * e[j][c]; }
;             const float r = 1.0f / sqrtf(wave_sum(ss) * (1.0f / DM) + EPS);
; #pragma unroll
;             for (int j = 0; j < 2; ++j)
; #pragma unroll
;                 for (int c = 0; c < 8; ++c) v[j][c] += (1.0f / (1.0f + expf(-f[j][c]))) * (e[j][c] * r * gp[j][c]);
.LBB0_261:
	s_and_b64 vcc, exec, s[36:37]
	s_cbranch_vccnz .Lrp_w10_a
	s_and_b64 vcc, exec, s[42:43]
	s_cbranch_vccnz .Lrp_w10_a
	s_and_b64 vcc, exec, s[38:39]
	s_cbranch_vccnz .Lrp_w9_a
	s_waitcnt vmcnt(8)
	s_branch .Lrp_wd_a
.Lrp_w9_a:
	s_waitcnt vmcnt(9)
	s_branch .Lrp_wd_a
.Lrp_w10_a:
	s_waitcnt vmcnt(10)
.Lrp_wd_a:
	v_cvt_f32_f16_sdwa v136, v44 dst_sel:DWORD dst_unused:UNUSED_PAD src0_sel:WORD_1
	v_cvt_f32_f16_e32 v132, v44
	v_cvt_f32_f16_e32 v133, v45
	v_cvt_f32_f16_sdwa v137, v45 dst_sel:DWORD dst_unused:UNUSED_PAD src0_sel:WORD_1
	v_cvt_f32_f16_sdwa v138, v46 dst_sel:DWORD dst_unused:UNUSED_PAD src0_sel:WORD_1
	v_cvt_f32_f16_e32 v134, v46
	v_cvt_f32_f16_e32 v135, v47
	v_cvt_f32_f16_sdwa v139, v47 dst_sel:DWORD dst_unused:UNUSED_PAD src0_sel:WORD_1
	v_cvt_f32_f16_sdwa v129, v48 dst_sel:DWORD dst_unused:UNUSED_PAD src0_sel:WORD_1
	v_cvt_f32_f16_e32 v128, v48
	v_cvt_f32_f16_sdwa v131, v49 dst_sel:DWORD dst_unused:UNUSED_PAD src0_sel:WORD_1
	v_cvt_f32_f16_e32 v130, v49
	v_cvt_f32_f16_sdwa v125, v50 dst_sel:DWORD dst_unused:UNUSED_PAD src0_sel:WORD_1
	v_cvt_f32_f16_e32 v124, v50
	v_cvt_f32_f16_sdwa v127, v51 dst_sel:DWORD dst_unused:UNUSED_PAD src0_sel:WORD_1
	v_cvt_f32_f16_e32 v126, v51
.LBB0_262:
	s_waitcnt vmcnt(10)
	v_and_b32_e32 v0, 0xffff0000, v72
	v_lshlrev_b32_e32 v149, 16, v73
	v_lshlrev_b32_e32 v148, 16, v72
	v_and_b32_e32 v151, 0xffff0000, v74
	v_and_b32_e32 v150, 0xffff0000, v73
	v_lshlrev_b32_e32 v153, 16, v75
	v_lshlrev_b32_e32 v152, 16, v74
	v_lshlrev_b32_e32 v156, 16, v76
	v_and_b32_e32 v157, 0xffff0000, v76
	v_lshlrev_b32_e32 v158, 16, v77
	v_and_b32_e32 v159, 0xffff0000, v77
	v_lshlrev_b32_e32 v160, 16, v78
	v_and_b32_e32 v161, 0xffff0000, v78
	v_and_b32_e32 v163, 0xffff0000, v75
	v_lshlrev_b32_e32 v162, 16, v79
	v_and_b32_e32 v154, 0xffff0000, v79
	s_and_b64 vcc, exec, s[36:37]
	s_cbranch_vccz .LBB0_302
	v_mul_f32_e32 v155, 0xbfb8aa3b, v148
	v_rndne_f32_e32 v165, v155
	v_sub_f32_e32 v166, v155, v165
	v_fma_f32 v155, v148, s22, -v155
	v_fmac_f32_e32 v155, 0xb2a5705f, v148
	v_add_f32_e32 v155, v166, v155
	v_exp_f32_e32 v155, v155
	v_cvt_i32_f32_e32 v165, v165
	v_cmp_nlt_f32_e32 vcc, s55, v148
	s_mov_b32 s4, 0xc2b17218
	v_lshlrev_b32_e32 v207, 16, v61
	v_ldexp_f32 v155, v155, v165
	v_cndmask_b32_e32 v155, 0, v155, vcc
	v_cmp_ngt_f32_e32 vcc, s4, v148
	v_lshlrev_b32_e32 v206, 16, v60
	v_and_b32_e32 v143, 0xffff0000, v60
	v_cndmask_b32_e32 v166, v235, v155, vcc
	v_mul_f32_e32 v155, 0xbfb8aa3b, v0
	v_rndne_f32_e32 v165, v155
	v_sub_f32_e32 v167, v155, v165
	v_fma_f32 v155, v0, s22, -v155
	v_fmac_f32_e32 v155, 0xb2a5705f, v0
	v_add_f32_e32 v155, v167, v155
	v_exp_f32_e32 v155, v155
	v_cvt_i32_f32_e32 v165, v165
	v_cmp_nlt_f32_e32 vcc, s55, v0
	v_and_b32_e32 v164, 0xffff0000, v67
	v_pk_mul_f32 v[208:209], v[206:207], v[206:207]
	v_ldexp_f32 v155, v155, v165
	v_mul_f32_e32 v165, 0xbfb8aa3b, v149
	v_rndne_f32_e32 v167, v165
	v_sub_f32_e32 v168, v165, v167
	v_fma_f32 v165, v149, s22, -v165
	v_fmac_f32_e32 v165, 0xb2a5705f, v149
	v_add_f32_e32 v165, v168, v165
	v_exp_f32_e32 v165, v165
	v_cvt_i32_f32_e32 v167, v167
	v_cndmask_b32_e32 v155, 0, v155, vcc
	v_cmp_ngt_f32_e32 vcc, s4, v0
	v_lshlrev_b32_e32 v203, 16, v63
	v_ldexp_f32 v165, v165, v167
	v_cndmask_b32_e32 v155, v235, v155, vcc
	v_cmp_nlt_f32_e32 vcc, s55, v149
	v_lshlrev_b32_e32 v202, 16, v62
	v_pk_mul_f32 v[204:205], v[202:203], v[202:203]
	v_cndmask_b32_e32 v165, 0, v165, vcc
	v_cmp_ngt_f32_e32 vcc, s4, v149
	v_lshlrev_b32_e32 v176, 16, v65
	v_and_b32_e32 v177, 0xffff0000, v65
	v_cndmask_b32_e32 v167, v235, v165, vcc
	v_pk_add_f32 v[166:167], v[166:167], 1.0 op_sel_hi:[1,0]
	v_pk_mul_f32 v[186:187], v[176:177], v[176:177]
	v_div_scale_f32 v165, s[14:15], v167, v167, 1.0
	v_rcp_f32_e32 v168, v165
	v_add_f32_e32 v155, 1.0, v155
	v_fma_f32 v169, -v165, v168, 1.0
	v_fmac_f32_e32 v168, v169, v168
	v_div_scale_f32 v169, vcc, 1.0, v167, 1.0
	v_mul_f32_e32 v170, v169, v168
	v_fma_f32 v171, -v165, v170, v169
	v_fmac_f32_e32 v170, v171, v168
	v_fma_f32 v165, -v165, v170, v169
	v_div_fmas_f32 v165, v165, v168, v170
	v_div_fixup_f32 v167, v165, v167, 1.0
	v_div_scale_f32 v165, s[14:15], v166, v166, 1.0
	v_rcp_f32_e32 v168, v165
	s_nop 0
	v_fma_f32 v169, -v165, v168, 1.0
	v_fmac_f32_e32 v168, v169, v168
	v_div_scale_f32 v169, vcc, 1.0, v166, 1.0
	v_mul_f32_e32 v170, v169, v168
	v_fma_f32 v171, -v165, v170, v169
	v_fmac_f32_e32 v170, v171, v168
	v_fma_f32 v165, -v165, v170, v169
	v_div_fmas_f32 v165, v165, v168, v170
	v_div_fixup_f32 v166, v165, v166, 1.0
	v_mul_f32_e32 v165, 0xbfb8aa3b, v150
	v_rndne_f32_e32 v168, v165
	v_sub_f32_e32 v169, v165, v168
	v_fma_f32 v165, v150, s22, -v165
	v_fmac_f32_e32 v165, 0xb2a5705f, v150
	v_add_f32_e32 v165, v169, v165
	v_exp_f32_e32 v165, v165
	v_cvt_i32_f32_e32 v168, v168
	v_cmp_nlt_f32_e32 vcc, s55, v150
	v_ldexp_f32 v165, v165, v168
	s_nop 0
	v_cndmask_b32_e32 v165, 0, v165, vcc
	v_cmp_ngt_f32_e32 vcc, s4, v150
	s_nop 1
	v_cndmask_b32_e32 v172, v235, v165, vcc
	v_mul_f32_e32 v165, 0xbfb8aa3b, v152
	v_rndne_f32_e32 v168, v165
	v_sub_f32_e32 v169, v165, v168
	v_fma_f32 v165, v152, s22, -v165
	v_fmac_f32_e32 v165, 0xb2a5705f, v152
	v_add_f32_e32 v165, v169, v165
	v_exp_f32_e32 v165, v165
	v_cvt_i32_f32_e32 v168, v168
	v_cmp_nlt_f32_e32 vcc, s55, v152
	v_ldexp_f32 v165, v165, v168
	s_nop 0
	v_cndmask_b32_e32 v165, 0, v165, vcc
	v_cmp_ngt_f32_e32 vcc, s4, v152
	s_nop 1
	v_cndmask_b32_e32 v168, v235, v165, vcc
	v_mul_f32_e32 v165, 0xbfb8aa3b, v151
	v_rndne_f32_e32 v169, v165
	v_sub_f32_e32 v170, v165, v169
	v_fma_f32 v165, v151, s22, -v165
	v_fmac_f32_e32 v165, 0xb2a5705f, v151
	v_add_f32_e32 v165, v170, v165
	v_exp_f32_e32 v165, v165
; #define UNPK_BF(dst, SRC_) do { const u32x4 t_ = (SRC_); dst[0] = bflo(t_.x); dst[1] = bfhi(t_.x); dst[2] = bflo(t_.y); dst[3] = bfhi(t_.y); dst[4] = bflo(t_.z); dst[5] = bfhi(t_.z); dst[6] = bflo(t_.w); dst[7] = bfhi(t_.w); } while (0)
; __device__ __forceinline__ void row_process(const RowArgs& R, int m, int lane, const RowRaw& q, const float (&gp)[2][8], const float (&gn)[2][8], const f32x4 bf, const LAS f32x4* afl) {
;     ...
;         if (R.F2) {
;             float e[2][8]; float ss = 0.f;
; #pragma unroll
;             for (int j = 0; j < 2; ++j) { UNPK_BF(e[j], q.e[j]);
; #pragma unroll
;                 for (int c = 0; c < 8; ++c) ss += e[j][c] * e[j][c]; }
;             const float r = 1.0f / sqrtf(wave_sum(ss) * (1.0f / DM) + EPS);
; #pragma unroll
;             for (int j = 0; j < 2; ++j)
; #pragma unroll
;                 for (int c = 0; c < 8; ++c) v[j][c] += (1.0f / (1.0f + expf(-f[j][c]))) * (e[j][c] * r * gp[j][c]);
	v_cvt_i32_f32_e32 v169, v169
	v_cmp_nlt_f32_e32 vcc, s55, v151
	v_ldexp_f32 v165, v165, v169
	s_nop 0
	v_cndmask_b32_e32 v165, 0, v165, vcc
	v_cmp_ngt_f32_e32 vcc, s4, v151
	s_nop 1
	v_cndmask_b32_e32 v173, v235, v165, vcc
	v_mul_f32_e32 v165, 0xbfb8aa3b, v153
	v_rndne_f32_e32 v169, v165
	v_sub_f32_e32 v170, v165, v169
	v_fma_f32 v165, v153, s22, -v165
	v_fmac_f32_e32 v165, 0xb2a5705f, v153
	v_add_f32_e32 v165, v170, v165
	v_exp_f32_e32 v165, v165
	v_cvt_i32_f32_e32 v169, v169
	v_cmp_nlt_f32_e32 vcc, s55, v153
	v_pk_add_f32 v[172:173], v[172:173], 1.0 op_sel_hi:[1,0]
	v_ldexp_f32 v165, v165, v169
	v_cndmask_b32_e32 v165, 0, v165, vcc
	v_cmp_ngt_f32_e32 vcc, s4, v153
	s_nop 1
	v_cndmask_b32_e32 v169, v235, v165, vcc
	v_pk_add_f32 v[168:169], v[168:169], 1.0 op_sel_hi:[1,0]
	s_nop 0
	v_div_scale_f32 v165, s[14:15], v169, v169, 1.0
	v_rcp_f32_e32 v170, v165
	s_nop 0
	v_fma_f32 v171, -v165, v170, 1.0
	v_fmac_f32_e32 v170, v171, v170
	v_div_scale_f32 v171, vcc, 1.0, v169, 1.0
	v_mul_f32_e32 v174, v171, v170
	v_fma_f32 v175, -v165, v174, v171
	v_fmac_f32_e32 v174, v175, v170
	v_fma_f32 v165, -v165, v174, v171
	v_div_fmas_f32 v165, v165, v170, v174
	v_div_fixup_f32 v169, v165, v169, 1.0
	v_div_scale_f32 v165, s[14:15], v168, v168, 1.0
	v_rcp_f32_e32 v170, v165
	s_nop 0
	v_fma_f32 v171, -v165, v170, 1.0
	v_fmac_f32_e32 v170, v171, v170
	v_div_scale_f32 v171, vcc, 1.0, v168, 1.0
	v_mul_f32_e32 v174, v171, v170
	v_fma_f32 v175, -v165, v174, v171
	v_fmac_f32_e32 v174, v175, v170
	v_fma_f32 v165, -v165, v174, v171
	v_div_fmas_f32 v165, v165, v170, v174
	v_div_fixup_f32 v168, v165, v168, 1.0
	v_mul_f32_e32 v165, 0xbfb8aa3b, v163
	v_rndne_f32_e32 v170, v165
	v_sub_f32_e32 v171, v165, v170
	v_fma_f32 v165, v163, s22, -v165
	v_fmac_f32_e32 v165, 0xb2a5705f, v163
	v_add_f32_e32 v165, v171, v165
	v_exp_f32_e32 v165, v165
	v_cvt_i32_f32_e32 v170, v170
	v_cmp_nlt_f32_e32 vcc, s55, v163
	v_and_b32_e32 v175, 0xffff0000, v66
	v_ldexp_f32 v165, v165, v170
	v_cndmask_b32_e32 v165, 0, v165, vcc
	v_cmp_ngt_f32_e32 vcc, s4, v163
	s_nop 1
	v_cndmask_b32_e32 v171, v235, v165, vcc
	v_mul_f32_e32 v165, 0xbfb8aa3b, v156
	v_rndne_f32_e32 v170, v165
	v_sub_f32_e32 v174, v165, v170
	v_fma_f32 v165, v156, s22, -v165
	v_fmac_f32_e32 v165, 0xb2a5705f, v156
	v_add_f32_e32 v165, v174, v165
	v_exp_f32_e32 v165, v165
	v_cvt_i32_f32_e32 v170, v170
	v_cmp_nlt_f32_e32 vcc, s55, v156
	v_ldexp_f32 v165, v165, v170
	s_nop 0
	v_cndmask_b32_e32 v165, 0, v165, vcc
	v_cmp_ngt_f32_e32 vcc, s4, v156
	s_nop 1
	v_cndmask_b32_e32 v182, v235, v165, vcc
	v_mul_f32_e32 v165, 0xbfb8aa3b, v157
	v_rndne_f32_e32 v170, v165
	v_sub_f32_e32 v174, v165, v170
	v_fma_f32 v165, v157, s22, -v165
	v_fmac_f32_e32 v165, 0xb2a5705f, v157
	v_add_f32_e32 v165, v174, v165
	v_exp_f32_e32 v165, v165
	v_cvt_i32_f32_e32 v170, v170
	v_cmp_nlt_f32_e32 vcc, s55, v157
	v_ldexp_f32 v165, v165, v170
	s_nop 0
	v_cndmask_b32_e32 v165, 0, v165, vcc
	v_cmp_ngt_f32_e32 vcc, s4, v157
	s_nop 1
	v_cndmask_b32_e32 v183, v235, v165, vcc
	v_mul_f32_e32 v165, 0xbfb8aa3b, v158
	v_rndne_f32_e32 v170, v165
	v_sub_f32_e32 v174, v165, v170
	v_fma_f32 v165, v158, s22, -v165
	v_fmac_f32_e32 v165, 0xb2a5705f, v158
	v_add_f32_e32 v165, v174, v165
	v_exp_f32_e32 v165, v165
	v_cvt_i32_f32_e32 v170, v170
	v_cmp_nlt_f32_e32 vcc, s55, v158
	v_pk_add_f32 v[182:183], v[182:183], 1.0 op_sel_hi:[1,0]
	v_ldexp_f32 v165, v165, v170
	v_cndmask_b32_e32 v165, 0, v165, vcc
	v_cmp_ngt_f32_e32 vcc, s4, v158
	s_nop 1
	v_cndmask_b32_e32 v178, v235, v165, vcc
	v_mul_f32_e32 v165, 0xbfb8aa3b, v159
	v_rndne_f32_e32 v170, v165
	v_sub_f32_e32 v174, v165, v170
	v_fma_f32 v165, v159, s22, -v165
	v_fmac_f32_e32 v165, 0xb2a5705f, v159
	v_add_f32_e32 v165, v174, v165
	v_exp_f32_e32 v165, v165
	v_cvt_i32_f32_e32 v170, v170
	v_cmp_nlt_f32_e32 vcc, s55, v159
	v_ldexp_f32 v165, v165, v170
	s_nop 0
	v_cndmask_b32_e32 v165, 0, v165, vcc
	v_cmp_ngt_f32_e32 vcc, s4, v159
	s_nop 1
	v_cndmask_b32_e32 v179, v235, v165, vcc
	v_mul_f32_e32 v165, 0xbfb8aa3b, v160
	v_rndne_f32_e32 v170, v165
	v_sub_f32_e32 v174, v165, v170
	v_fma_f32 v165, v160, s22, -v165
	v_fmac_f32_e32 v165, 0xb2a5705f, v160
	v_add_f32_e32 v165, v174, v165
	v_exp_f32_e32 v165, v165
	v_cvt_i32_f32_e32 v170, v170
	v_cmp_nlt_f32_e32 vcc, s55, v160
	v_pk_add_f32 v[178:179], v[178:179], 1.0 op_sel_hi:[1,0]
	v_ldexp_f32 v165, v165, v170
	v_cndmask_b32_e32 v165, 0, v165, vcc
	v_cmp_ngt_f32_e32 vcc, s4, v160
	s_nop 1
	v_cndmask_b32_e32 v194, v235, v165, vcc
	v_mul_f32_e32 v165, 0xbfb8aa3b, v161
	v_rndne_f32_e32 v170, v165
	v_sub_f32_e32 v174, v165, v170
	v_fma_f32 v165, v161, s22, -v165
	v_fmac_f32_e32 v165, 0xb2a5705f, v161
	v_add_f32_e32 v165, v174, v165
	v_exp_f32_e32 v165, v165
	v_cvt_i32_f32_e32 v170, v170
	v_cmp_nlt_f32_e32 vcc, s55, v161
	v_lshlrev_b32_e32 v174, 16, v66
	v_pk_mul_f32 v[184:185], v[174:175], v[174:175]
	v_ldexp_f32 v165, v165, v170
	v_cndmask_b32_e32 v165, 0, v165, vcc
	v_cmp_ngt_f32_e32 vcc, s4, v161
	s_nop 1
	v_cndmask_b32_e32 v195, v235, v165, vcc
	v_div_scale_f32 v165, s[14:15], v179, v179, 1.0
	v_rcp_f32_e32 v170, v165
	s_nop 0
	v_fma_f32 v180, -v165, v170, 1.0
	v_fmac_f32_e32 v170, v180, v170
	v_div_scale_f32 v180, vcc, 1.0, v179, 1.0
	v_mul_f32_e32 v181, v180, v170
	v_fma_f32 v188, -v165, v181, v180
	v_fmac_f32_e32 v181, v188, v170
	v_fma_f32 v165, -v165, v181, v180
	v_div_fmas_f32 v165, v165, v170, v181
	v_div_fixup_f32 v179, v165, v179, 1.0
	v_div_scale_f32 v165, s[14:15], v178, v178, 1.0
	v_rcp_f32_e32 v170, v165
	s_nop 0
	v_fma_f32 v180, -v165, v170, 1.0
	v_fmac_f32_e32 v170, v180, v170
	v_div_scale_f32 v180, vcc, 1.0, v178, 1.0
	v_mul_f32_e32 v181, v180, v170
	v_fma_f32 v188, -v165, v181, v180
; #define UNPK_BF(dst, SRC_) do { const u32x4 t_ = (SRC_); dst[0] = bflo(t_.x); dst[1] = bfhi(t_.x); dst[2] = bflo(t_.y); dst[3] = bfhi(t_.y); dst[4] = bflo(t_.z); dst[5] = bfhi(t_.z); dst[6] = bflo(t_.w); dst[7] = bfhi(t_.w); } while (0)
; __device__ __forceinline__ void row_process(const RowArgs& R, int m, int lane, const RowRaw& q, const float (&gp)[2][8], const float (&gn)[2][8], const f32x4 bf, const LAS f32x4* afl) {
;     ...
;         if (R.F2) {
;             float e[2][8]; float ss = 0.f;
; #pragma unroll
;             for (int j = 0; j < 2; ++j) { UNPK_BF(e[j], q.e[j]);
; #pragma unroll
;                 for (int c = 0; c < 8; ++c) ss += e[j][c] * e[j][c]; }
;             const float r = 1.0f / sqrtf(wave_sum(ss) * (1.0f / DM) + EPS);
; #pragma unroll
;             for (int j = 0; j < 2; ++j)
; #pragma unroll
;                 for (int c = 0; c < 8; ++c) v[j][c] += (1.0f / (1.0f + expf(-f[j][c]))) * (e[j][c] * r * gp[j][c]);
	v_fmac_f32_e32 v181, v188, v170
	v_fma_f32 v165, -v165, v181, v180
	v_div_fmas_f32 v165, v165, v170, v181
	v_div_fixup_f32 v178, v165, v178, 1.0
	v_div_scale_f32 v165, s[14:15], v183, v183, 1.0
	v_rcp_f32_e32 v170, v165
	v_lshlrev_b32_e32 v180, 16, v64
	v_and_b32_e32 v181, 0xffff0000, v64
	v_pk_mul_f32 v[192:193], v[180:181], v[180:181]
	v_fma_f32 v188, -v165, v170, 1.0
	v_fmac_f32_e32 v170, v188, v170
	v_div_scale_f32 v188, vcc, 1.0, v183, 1.0
	v_mul_f32_e32 v189, v188, v170
	v_fma_f32 v190, -v165, v189, v188
	v_fmac_f32_e32 v189, v190, v170
	v_fma_f32 v165, -v165, v189, v188
	v_div_fmas_f32 v165, v165, v170, v189
	v_div_fixup_f32 v183, v165, v183, 1.0
	v_div_scale_f32 v165, s[14:15], v182, v182, 1.0
	v_rcp_f32_e32 v170, v165
	s_nop 0
	v_fma_f32 v188, -v165, v170, 1.0
	v_fmac_f32_e32 v170, v188, v170
	v_div_scale_f32 v188, vcc, 1.0, v182, 1.0
	v_mul_f32_e32 v189, v188, v170
	v_fma_f32 v190, -v165, v189, v188
	v_fmac_f32_e32 v189, v190, v170
	v_fma_f32 v165, -v165, v189, v188
	v_div_fmas_f32 v165, v165, v170, v189
	v_div_fixup_f32 v182, v165, v182, 1.0
	v_div_scale_f32 v165, s[14:15], v173, v173, 1.0
	v_rcp_f32_e32 v170, v165
	v_and_b32_e32 v189, 0xffff0000, v62
	v_and_b32_e32 v188, 0xffff0000, v61
	v_pk_mul_f32 v[198:199], v[188:189], v[188:189]
	v_fma_f32 v190, -v165, v170, 1.0
	v_fmac_f32_e32 v170, v190, v170
	v_div_scale_f32 v190, vcc, 1.0, v173, 1.0
	v_mul_f32_e32 v191, v190, v170
	v_fma_f32 v197, -v165, v191, v190
	v_fmac_f32_e32 v191, v197, v170
	v_fma_f32 v165, -v165, v191, v190
	v_div_fmas_f32 v165, v165, v170, v191
	v_div_fixup_f32 v191, v165, v173, 1.0
	v_div_scale_f32 v165, s[14:15], v172, v172, 1.0
	v_rcp_f32_e32 v170, v165
	s_nop 0
	v_fma_f32 v173, -v165, v170, 1.0
	v_fmac_f32_e32 v170, v173, v170
	v_div_scale_f32 v173, vcc, 1.0, v172, 1.0
	v_mul_f32_e32 v190, v173, v170
	v_fma_f32 v197, -v165, v190, v173
	v_fmac_f32_e32 v190, v197, v170
	v_fma_f32 v165, -v165, v190, v173
	v_div_fmas_f32 v165, v165, v170, v190
	v_div_fixup_f32 v190, v165, v172, 1.0
	v_pk_add_f32 v[172:173], v[194:195], 1.0 op_sel_hi:[1,0]
	s_nop 0
	v_div_scale_f32 v165, s[14:15], v173, v173, 1.0
	v_rcp_f32_e32 v170, v165
	s_nop 0
	v_fma_f32 v194, -v165, v170, 1.0
	v_fmac_f32_e32 v170, v194, v170
	v_div_scale_f32 v194, vcc, 1.0, v173, 1.0
	v_mul_f32_e32 v195, v194, v170
	v_fma_f32 v197, -v165, v195, v194
	v_fmac_f32_e32 v195, v197, v170
	v_fma_f32 v165, -v165, v195, v194
	v_div_fmas_f32 v165, v165, v170, v195
	v_div_fixup_f32 v173, v165, v173, 1.0
	v_div_scale_f32 v165, s[14:15], v172, v172, 1.0
	v_rcp_f32_e32 v170, v165
	s_nop 0
	v_fma_f32 v194, -v165, v170, 1.0
	v_fmac_f32_e32 v170, v194, v170
	v_div_scale_f32 v194, vcc, 1.0, v172, 1.0
	v_mul_f32_e32 v195, v194, v170
	v_fma_f32 v197, -v165, v195, v194
	v_fmac_f32_e32 v195, v197, v170
	v_fma_f32 v165, -v165, v195, v194
	v_div_fmas_f32 v165, v165, v170, v195
	v_div_fixup_f32 v172, v165, v172, 1.0
	v_mul_f32_e32 v165, 0xbfb8aa3b, v162
	v_rndne_f32_e32 v170, v165
	v_sub_f32_e32 v194, v165, v170
	v_fma_f32 v165, v162, s22, -v165
	v_fmac_f32_e32 v165, 0xb2a5705f, v162
	v_add_f32_e32 v165, v194, v165
	v_exp_f32_e32 v165, v165
	v_cvt_i32_f32_e32 v170, v170
	v_cmp_nlt_f32_e32 vcc, s55, v162
	v_lshlrev_b32_e32 v194, 16, v67
	v_and_b32_e32 v195, 0xffff0000, v63
	v_ldexp_f32 v165, v165, v170
	v_cndmask_b32_e32 v165, 0, v165, vcc
	v_cmp_ngt_f32_e32 vcc, s4, v162
	s_nop 1
	v_cndmask_b32_e32 v170, v235, v165, vcc
	v_mov_b32_e32 v165, v194
	v_pk_mul_f32 v[200:201], v[164:165], v[164:165]
	v_fma_f32 v165, v143, v143, v208
	v_add_f32_e32 v165, v209, v165
	v_add_f32_e32 v165, v198, v165
	v_add_f32_e32 v165, v204, v165
	v_add_f32_e32 v165, v199, v165
	v_add_f32_e32 v165, v205, v165
	v_fmac_f32_e32 v165, v195, v195
	v_add_f32_e32 v165, v192, v165
	v_add_f32_e32 v165, v193, v165
	v_add_f32_e32 v165, v186, v165
	v_add_f32_e32 v165, v187, v165
	v_add_f32_e32 v165, v184, v165
	v_add_f32_e32 v165, v185, v165
	v_add_f32_e32 v165, v201, v165
	v_add_f32_e32 v165, v200, v165
	v_pk_add_f32 v[170:171], v[170:171], 1.0 op_sel_hi:[1,0]
	v_mov_b32_e32 v193, v164
	v_add_f32_dpp v165, v165, v165 quad_perm:[1,0,3,2] row_mask:0xf bank_mask:0xf bound_ctrl:1
	s_nop 1
	v_add_f32_dpp v165, v165, v165 quad_perm:[2,3,0,1] row_mask:0xf bank_mask:0xf bound_ctrl:1
	s_nop 1
	v_add_f32_dpp v165, v165, v165 row_half_mirror row_mask:0xf bank_mask:0xf bound_ctrl:1
	s_nop 1
	v_add_f32_dpp v165, v165, v165 row_mirror row_mask:0xf bank_mask:0xf bound_ctrl:1
	s_nop 0
	v_readlane_b32 s1, v165, 16
	v_readlane_b32 s3, v165, 48
	v_readlane_b32 s14, v165, 0
	v_readlane_b32 s15, v165, 32
	v_mov_b32_e32 v184, s1
; __device__ __forceinline__ void row_process(const RowArgs& R, int m, int lane, const RowRaw& q, const float (&gp)[2][8], const float (&gn)[2][8], const f32x4 bf, const LAS f32x4* afl) {
;     ...
;             const float r = 1.0f / sqrtf(wave_sum(ss) * (1.0f / DM) + EPS);
; #pragma unroll
;             for (int j = 0; j < 2; ++j)
; #pragma unroll
;                 for (int c = 0; c < 8; ++c) v[j][c] += (1.0f / (1.0f + expf(-f[j][c]))) * (e[j][c] * r * gp[j][c]);
	v_mov_b32_e32 v185, s3
	v_pk_add_f32 v[184:185], s[14:15], v[184:185]
	s_nop 0
	v_add_f32_e32 v165, v184, v185
	v_fmamk_f32 v165, v165, 0x3a800000, v229
	v_cmp_gt_f32_e32 vcc, s59, v165
	v_mul_f32_e32 v184, 0x4f800000, v165
	s_nop 0
	v_cndmask_b32_e32 v165, v165, v184, vcc
	v_sqrt_f32_e32 v184, v165
	s_nop 0
	v_add_u32_e32 v185, -1, v184
	v_fma_f32 v186, -v185, v184, v165
	v_cmp_ge_f32_e64 s[14:15], 0, v186
	v_add_u32_e32 v186, 1, v184
	s_nop 0
	v_cndmask_b32_e64 v185, v184, v185, s[14:15]
	v_fma_f32 v184, -v186, v184, v165
	v_cmp_lt_f32_e64 s[14:15], 0, v184
	s_nop 1
	v_cndmask_b32_e64 v184, v185, v186, s[14:15]
	v_mul_f32_e32 v185, 0x37800000, v184
	v_cndmask_b32_e32 v184, v184, v185, vcc
	v_cmp_class_f32_e32 vcc, v165, v230
	s_nop 1
	v_cndmask_b32_e32 v165, v184, v165, vcc
	v_div_scale_f32 v184, s[14:15], v165, v165, 1.0
	v_rcp_f32_e32 v185, v184
	s_nop 0
	v_fma_f32 v186, -v184, v185, 1.0
	v_fmac_f32_e32 v185, v186, v185
	v_div_scale_f32 v186, vcc, 1.0, v165, 1.0
	v_mul_f32_e32 v187, v186, v185
	v_fma_f32 v192, -v184, v187, v186
	v_fmac_f32_e32 v187, v192, v185
	v_fma_f32 v184, -v184, v187, v186
	v_div_fmas_f32 v184, v184, v185, v187
	v_div_fixup_f32 v187, v184, v165, 1.0
	v_div_scale_f32 v165, s[14:15], v155, v155, 1.0
	v_rcp_f32_e32 v184, v165
	v_mul_f32_e32 v143, v187, v143
	v_mov_b32_e32 v198, v187
	v_pk_mul_f32 v[176:177], v[198:199], v[176:177] op_sel_hi:[0,1]
	v_fma_f32 v185, -v165, v184, 1.0
	v_fmac_f32_e32 v184, v185, v184
	v_div_scale_f32 v185, vcc, 1.0, v155, 1.0
	v_mul_f32_e32 v186, v185, v184
	v_fma_f32 v192, -v165, v186, v185
	v_fmac_f32_e32 v186, v192, v184
	v_fma_f32 v165, -v165, v186, v185
	v_div_fmas_f32 v165, v165, v184, v186
	v_mul_f32_e32 v192, v196, v143
	v_div_scale_f32 v143, s[14:15], v171, v171, 1.0
	v_div_fixup_f32 v186, v165, v155, 1.0
	v_rcp_f32_e32 v155, v143
	v_pk_mul_f32 v[184:185], v[198:199], v[206:207] op_sel_hi:[0,1]
	v_pk_mul_f32 v[184:185], v[6:7], v[184:185]
	v_pk_mul_f32 v[176:177], v[22:23], v[176:177]
	v_pk_mul_f32 v[166:167], v[166:167], v[184:185]
	v_pk_mul_f32 v[184:185], v[198:199], v[188:189] op_sel_hi:[0,1]
	v_pk_mul_f32 v[188:189], v[198:199], v[202:203] op_sel_hi:[0,1]
	v_fma_f32 v165, -v143, v155, 1.0
	v_pk_mul_f32 v[188:189], v[12:13], v[188:189]
	v_fmac_f32_e32 v155, v165, v155
	v_div_scale_f32 v165, vcc, 1.0, v171, 1.0
	v_pk_mul_f32 v[168:169], v[168:169], v[188:189]
	v_mul_f32_e32 v188, v165, v155
	v_fma_f32 v189, -v143, v188, v165
	v_fmac_f32_e32 v188, v189, v155
	v_fma_f32 v143, -v143, v188, v165
	v_div_fmas_f32 v143, v143, v155, v188
	v_div_fixup_f32 v189, v143, v171, 1.0
	v_div_scale_f32 v143, s[14:15], v170, v170, 1.0
	v_rcp_f32_e32 v155, v143
	v_pk_mul_f32 v[176:177], v[178:179], v[176:177]
	v_pk_mul_f32 v[184:185], v[140:141], v[184:185]
	v_pk_mul_f32 v[174:175], v[198:199], v[174:175] op_sel_hi:[0,1]
	v_fma_f32 v165, -v143, v155, 1.0
	v_fmac_f32_e32 v155, v165, v155
	v_div_scale_f32 v165, vcc, 1.0, v170, 1.0
	v_mul_f32_e32 v171, v165, v155
	v_fma_f32 v188, -v143, v171, v165
	v_fmac_f32_e32 v171, v188, v155
	v_fma_f32 v143, -v143, v171, v165
	v_div_fmas_f32 v143, v143, v155, v171
	v_div_fixup_f32 v188, v143, v170, 1.0
	v_mul_f32_e32 v143, 0xbfb8aa3b, v154
	v_rndne_f32_e32 v155, v143
	v_sub_f32_e32 v165, v143, v155
	v_fma_f32 v143, v154, s22, -v143
	v_fmac_f32_e32 v143, 0xb2a5705f, v154
	v_add_f32_e32 v143, v165, v143
	v_exp_f32_e32 v143, v143
	v_cvt_i32_f32_e32 v155, v155
	v_cmp_nlt_f32_e32 vcc, s55, v154
	v_pk_mul_f32 v[170:171], v[198:199], v[194:195] op_sel_hi:[0,1]
	v_pk_mul_f32 v[184:185], v[190:191], v[184:185]
	v_ldexp_f32 v143, v143, v155
	v_cndmask_b32_e32 v143, 0, v143, vcc
	v_cmp_ngt_f32_e32 vcc, s4, v154
	v_pk_mul_f32 v[190:191], v[14:15], v[170:171]
	v_pk_mul_f32 v[170:171], v[198:199], v[180:181] op_sel_hi:[0,1]
	v_cndmask_b32_e32 v143, v235, v143, vcc
	v_add_f32_e32 v143, 1.0, v143
	v_div_scale_f32 v155, s[14:15], v143, v143, 1.0
	v_rcp_f32_e32 v165, v155
	v_pk_mul_f32 v[170:171], v[20:21], v[170:171]
	v_pk_mul_f32 v[174:175], v[28:29], v[174:175]
	v_pk_mul_f32 v[170:171], v[182:183], v[170:171]
	v_fma_f32 v178, -v155, v165, 1.0
	v_fmac_f32_e32 v165, v178, v165
	v_div_scale_f32 v178, vcc, 1.0, v143, 1.0
	v_mul_f32_e32 v179, v178, v165
	v_fma_f32 v180, -v155, v179, v178
	v_fmac_f32_e32 v179, v180, v165
	v_fma_f32 v155, -v155, v179, v178
	v_div_fmas_f32 v155, v155, v165, v179
	v_pk_mul_f32 v[174:175], v[172:173], v[174:175]
	v_pk_mul_f32 v[172:173], v[188:189], v[190:191]
	v_div_fixup_f32 v143, v155, v143, 1.0
	v_pk_mul_f32 v[164:165], v[186:187], v[192:193]
	s_cbranch_execnz .LBB0_265

; __device__ __forceinline__ void row_pass(const RowArgs& R, int gw, int NGW, int lane, LAS unsigned char* lds, int tid) {
;     ...
;     for (int m = gw; m < M; m += 2 * NGW) {
;         const int m1 = m + NGW, m2 = m + 2 * NGW;
;         if (m1 < M) row_load(R, m1, lane, qb);
;         row_process(R, m, lane, qa, gp, gn, bf, afl);
;         if (m2 < M) row_load(R, m2, lane, qa);
;         if (m1 < M) row_process(R, m1, lane, qb, gp, gn, bf, afl);
;     }
.LBB0_278:
	v_lshl_add_u64 v[48:49], v[148:149], 1, s[46:47]
	global_load_dwordx4 v[44:47], v[48:49], off nt
	s_nop 0
	global_load_dwordx4 v[48:51], v[48:49], off offset:1024 nt
	v_mov_b64_e32 v[134:135], v[58:59]
	v_mov_b64_e32 v[138:139], v[54:55]
	v_mov_b64_e32 v[126:127], v[42:43]
	v_mov_b64_e32 v[130:131], v[38:39]
	v_mov_b64_e32 v[132:133], v[56:57]
	v_mov_b64_e32 v[136:137], v[52:53]
	v_mov_b64_e32 v[124:125], v[40:41]
	v_mov_b64_e32 v[128:129], v[36:37]

; __device__ __forceinline__ void row_pass(const RowArgs& R, int gw, int NGW, int lane, LAS unsigned char* lds, int tid) {
;     ...
;     for (int m = gw; m < M; m += 2 * NGW) {
;         const int m1 = m + NGW, m2 = m + 2 * NGW;
;         if (m1 < M) row_load(R, m1, lane, qb);
;         row_process(R, m, lane, qa, gp, gn, bf, afl);
;         if (m2 < M) row_load(R, m2, lane, qa);
;         if (m1 < M) row_process(R, m1, lane, qb, gp, gn, bf, afl);
;     }
.LBB0_283:
	s_and_b64 vcc, exec, s[12:13]
	s_cbranch_vccnz .LBB0_284
	s_waitcnt vmcnt(4)
	v_mov_b64_e32 v[36:37], v[128:129]
	v_mov_b64_e32 v[40:41], v[124:125]
	s_waitcnt vmcnt(2)
	v_mov_b64_e32 v[52:53], v[136:137]
	v_mov_b64_e32 v[56:57], v[132:133]
	v_mov_b64_e32 v[38:39], v[130:131]
	v_mov_b64_e32 v[42:43], v[126:127]
	v_mov_b64_e32 v[54:55], v[138:139]
	v_mov_b64_e32 v[58:59], v[134:135]

; __device__ __forceinline__ void row_pass(const RowArgs& R, int gw, int NGW, int lane, LAS unsigned char* lds, int tid) {
;     ...
;     for (int m = gw; m < M; m += 2 * NGW) {
;         const int m1 = m + NGW, m2 = m + 2 * NGW;
;         if (m1 < M) row_load(R, m1, lane, qb);
;         row_process(R, m, lane, qa, gp, gn, bf, afl);
;         if (m2 < M) row_load(R, m2, lane, qa);
;         if (m1 < M) row_process(R, m1, lane, qb, gp, gn, bf, afl);
;     }
.Lrp_skipl1:
	s_waitcnt vmcnt(0)
	s_branch .LBB0_259

; #define PG8_STAGE(bufoff, gbase, voff) do { _Pragma("unroll") for (int _i = 0; _i < 2; ++_i) \
;         __builtin_amdgcn_global_load_lds((const unsigned*)((const char*)(gbase) + (voff)[_i]), (PG8_LAS unsigned*)(lds + (bufoff) + ldsw + _i * 8192), 16, 0, 0); } while (0)
; #define PG8_WAIT_V(n) asm volatile("s_waitcnt vmcnt(" #n ")" ::: "memory")
; #define PG8_BAR __builtin_amdgcn_s_barrier()
; template <class Epi, class Sched, bool ALIGN_EPI = false, bool SP2 = false>
; __device__ __forceinline__ void gemm_phase(PG8_LAS unsigned char* lds, const Gemm g, const Sched& S, const Epi& E) {
;     ...
;     for (int i = 0; i < 2; ++i) { int R, C; stage_rc(tid * 16 + i * 8192, R, C); const int Rb = Epi::PERM ? ((R & ~31) + perm32(R & 31)) : R;
;         voffA[i] = (unsigned)(R * K + C) * 2u; voffB[i] = (unsigned)(Rb * K + C) * 2u; }
;     const size_t kstep = (size_t)(BK * 2);
;     const size_t hstep = (size_t)HALF * K * 2;
;     const size_t tstep = 2 * hstep;
;     const unsigned ldsw = (unsigned)wid * 1024u;
;     const int aoff = lds_byte(wr * 64 + fr, fq * 8), boff = lds_byte(wc * 32 + fr, fq * 8);
;     ...
;     Unit cur, nxt; int ui = 0;
;     if (!S.next(0, cur)) return;
;     f32x4 acc[2][2][4][2];
; #pragma unroll
;     for (int a = 0; a < 2; ++a)
; #pragma unroll
;         for (int b = 0; b < 2; ++b)
; #pragma unroll
;             for (int m = 0; m < 4; ++m)
; #pragma unroll
;                 for (int n = 0; n < 2; ++n) acc[a][b][m][n] = (f32x4){0.f, 0.f, 0.f, 0.f};
;     bf16x8 At[4][2], B0[2][2], B1[2][2];
;     const char* cA = (const char*)g.A + (size_t)cur.pm * tstep; const char* cB = (const char*)g.Bt + (size_t)cur.pn * tstep;
;     S.a_ready(cur);
;     if constexpr (SP2) {
;         PG8_STAGE(PG8_SB(0, 0), cB, voffB); PG8_STAGE(PG8_SB(0, 1), cB + hstep, voffB); PG8_STAGE(PG8_SA(0, 0), cA, voffA); PG8_STAGE(PG8_SA(0, 1), cA + hstep, voffA);
;         if (wr == 1) PG8_BAR;
;         PG8_WAIT_V(2); PG8_BAR;
;         PG8_STAGE(PG8_SB(1, 0), cB + kstep, voffB); PG8_STAGE(PG8_SA(1, 0), cA + kstep, voffA); PG8_STAGE(PG8_SB(1, 1), cB + hstep + kstep, voffB);
;         PG8_WAIT_V(6); PG8_BAR;
;     } else {
;         PG8_STAGE(PG8_SB(0, 0), cB, voffB); PG8_STAGE(PG8_SA(0, 0), cA, voffA); PG8_STAGE(PG8_SB(0, 1), cB + hstep, voffB); PG8_STAGE(PG8_SA(0, 1), cA + hstep, voffA);
.LBB0_499:
	v_mov_b32_e32 v0, v228
	s_mov_b32 s30, s2
	v_mov_b32_e32 v10, v228
	s_cmpk_gt_i32 s30, 0x15ff
	v_readfirstlane_b32 s1, v10
	s_cbranch_scc1 .LBB0_515
	v_lshrrev_b32_e32 v242, 3, v228
	v_and_b32_e32 v243, 7, v228
	v_and_b32_e32 v244, 6, v242
	v_xor_b32_e32 v243, v243, v244
	v_lshlrev_b32_e32 v243, 3, v243
	v_lshlrev_b32_e32 v245, 10, v242
	v_add_lshl_u32 v232, v245, v243, 1
	v_add_u32_e32 v246, 64, v242
	v_lshlrev_b32_e32 v246, 10, v246
	v_add_lshl_u32 v233, v246, v243, 1
	v_and_b32_e32 v247, 31, v242
	v_lshrrev_b32_e32 v248, 4, v247
	v_and_b32_e32 v249, 15, v247
	v_lshrrev_b32_e32 v250, 2, v249
	v_lshlrev_b32_e32 v250, 3, v250
	v_and_b32_e32 v249, 3, v249
	v_lshl_add_u32 v250, v248, 2, v250
	v_add_u32_e32 v250, v250, v249
	v_and_b32_e32 v247, 32, v242
	v_add_u32_e32 v250, v250, v247
	v_lshlrev_b32_e32 v251, 10, v250
	v_add_lshl_u32 v236, v251, v243, 1
	v_add_u32_e32 v250, 64, v250
	v_lshlrev_b32_e32 v251, 10, v250
	v_add_lshl_u32 v237, v251, v243, 1
	v_and_b32_e32 v244, 15, v228
	v_bfe_u32 v245, v228, 4, 2
	v_and_b32_e32 v246, 6, v244
	v_xor_b32_e32 v246, v246, v245
	v_lshlrev_b32_e32 v246, 4, v246
	v_and_b32_e32 v247, 7, v244
	v_lshl_add_u32 v246, v247, 7, v246
	v_lshrrev_b32_e32 v247, 3, v244
	v_lshl_add_u32 v246, v247, 10, v246
	v_lshrrev_b32_e32 v247, 8, v228
	v_lshl_add_u32 v227, v247, 13, v246
	v_xor_b32_e32 v225, 64, v227
	v_bfe_u32 v247, v228, 6, 2
	v_lshl_add_u32 v252, v247, 12, v246
	v_xor_b32_e32 v226, 64, v252
	v_lshlrev_b32_e32 v0, 4, v10
	v_add_u32_e32 v2, 0x2000, v0
	v_ashrrev_i32_e32 v3, 31, v2
	v_lshrrev_b32_e32 v3, 22, v3
	v_add_u32_e32 v3, v2, v3
	v_ashrrev_i32_e32 v11, 10, v3
	v_mul_i32_i24_e32 v3, 0x400, v11
	v_sub_u32_e32 v2, v2, v3
	v_lshrrev_b32_e32 v3, 4, v2
	v_bitop3_b32 v2, v3, v2, 32 bitop3:0x6c
	v_ashrrev_i32_e32 v3, 31, v2
	v_lshrrev_b32_e32 v3, 26, v3
	v_add_u32_e32 v3, v2, v3
	v_lshlrev_b32_e32 v4, 3, v11
	s_cmp_eq_u32 s0, 1
	s_mov_b32 s0, 0x100000
	v_ashrrev_i32_e32 v12, 6, v3
	v_and_b32_e32 v4, -16, v4
	s_cselect_b32 s0, s0, 0x2380000
	v_readlane_b32 s6, v255, 16
	v_add_u32_e32 v4, v12, v4
	s_add_u32 s0, s6, s0
	v_and_b32_e32 v5, 3, v12
	s_mov_b32 s6, 0x1fffe0
	v_lshrrev_b32_e32 v6, 2, v4
	v_lshlrev_b32_e32 v7, 1, v4
	v_and_b32_e32 v3, 0xc0, v3
	v_and_or_b32 v5, v4, s6, v5
	v_and_b32_e32 v6, 4, v6
	v_and_b32_e32 v7, 24, v7
	v_sub_u32_e32 v2, v2, v3
	v_or3_b32 v5, v5, v6, v7
	v_lshlrev_b32_e32 v6, 5, v11
	v_ashrrev_i16_sdwa v2, v234, sext(v2) dst_sel:DWORD dst_unused:UNUSED_PAD src0_sel:DWORD src1_sel:BYTE_0
	v_and_b32_e32 v6, 32, v6
	v_bfe_i32 v13, v2, 0, 16
	v_add_lshl_u32 v2, v6, v13, 1
	v_mov_b32_e32 v130, v237
	v_mov_b32_e32 v132, v233
	v_bfe_i32 v2, v10, 27, 1
	v_lshrrev_b32_e32 v2, 22, v2
	v_add_u32_e32 v2, v0, v2
	v_and_b32_e32 v2, 0xfffffc00, v2
	v_sub_u32_e32 v0, v0, v2
	v_lshrrev_b32_e32 v2, 4, v0
	v_ashrrev_i32_e32 v3, 31, v10
	v_bitop3_b32 v0, v2, v0, 32 bitop3:0x6c
	v_lshrrev_b32_e32 v3, 26, v3
	v_ashrrev_i32_e32 v2, 31, v0
	v_add_u32_e32 v3, v10, v3
	v_lshrrev_b32_e32 v2, 26, v2
	s_waitcnt vmcnt(0)
	v_ashrrev_i32_e32 v15, 6, v3
	v_add_u32_e32 v2, v0, v2
	v_lshlrev_b32_e32 v3, 3, v15
	v_readlane_b32 s7, v255, 17
	v_ashrrev_i32_e32 v14, 6, v2
	v_and_b32_e32 v3, -16, v3
	s_addc_u32 s44, s7, 0
	v_add_u32_e32 v3, v14, v3
	v_and_b32_e32 v4, 3, v14
	s_ashr_i32 s46, s30, 31
	v_and_or_b32 v4, v3, s6, v4
	s_lshr_b32 s6, s46, 29
	s_add_i32 s6, s30, s6
	s_waitcnt lgkmcnt(0)
	s_ashr_i32 s3, s1, 6
	s_ashr_i32 s7, s6, 3
	s_and_b32 s6, s6, -8
	s_ashr_i32 s4, s1, 8
	s_lshl_b32 s45, s3, 10
	s_sub_i32 s6, s30, s6
	s_cmp_lt_i32 s6, 0
	s_movk_i32 s8, 0x2c1
	s_cselect_b32 s8, s8, 0x2c0
	s_mul_i32 s6, s6, s8
	s_add_i32 s6, s6, s7
	s_mul_hi_i32 s7, s6, 0x2e8ba2e9
	s_lshr_b32 s8, s7, 31
	s_ashr_i32 s7, s7, 5
	s_add_i32 s7, s7, s8
	s_lshl_b32 s8, s7, 3
	s_mulk_i32 s7, 0xb0
	s_sub_i32 s7, s6, s7
	s_bfe_u32 s6, s7, 0x3001c
	s_add_i32 s9, s7, s6
	s_sext_i32_i16 s6, s9
	s_and_b32 s9, s9, 0xfff8
	s_sub_i32 s7, s7, s9
	s_sext_i32_i16 s7, s7
	v_lshrrev_b32_e32 v5, 2, v3
	v_lshlrev_b32_e32 v6, 1, v3
	v_and_b32_e32 v2, 0xc0, v2
	s_lshr_b32 s6, s6, 3
	s_add_i32 s34, s8, s7
	v_and_b32_e32 v5, 4, v5
	v_and_b32_e32 v6, 24, v6
	v_sub_u32_e32 v0, v0, v2
	s_ashr_i32 s35, s34, 31
	s_bfe_i64 s[10:11], s[6:7], 0x100000
	v_or3_b32 v4, v4, v5, v6
	v_lshlrev_b32_e32 v5, 5, v15
	v_ashrrev_i16_sdwa v0, v234, sext(v0) dst_sel:DWORD dst_unused:UNUSED_PAD src0_sel:DWORD src1_sel:BYTE_0
	s_lshl_b64 s[8:9], s[34:35], 19
	s_lshl_b64 s[10:11], s[10:11], 19
	s_mov_b64 s[74:75], s[38:39]
	v_and_b32_e32 v5, 32, v5
	v_bfe_i32 v16, v0, 0, 16
	s_add_u32 s38, s0, s10
	v_add_lshl_u32 v2, v5, v16, 1
	s_addc_u32 s39, s44, s11
	s_add_i32 s47, s45, 0
	v_mov_b32_e32 v0, v236
	s_add_i32 m0, s47, 0x10000
	v_mov_b32_e32 v134, v232
	global_load_lds_dwordx4 v0, s[38:39]
	s_add_i32 m0, s47, 0x12000
	s_add_u32 s10, s38, 0x40000
	global_load_lds_dwordx4 v130, s[38:39]
	s_addc_u32 s11, s39, 0
	s_add_i32 m0, s47, 0x14000
	s_load_dword s67, s[90:91], 0x0
	global_load_lds_dwordx4 v0, s[10:11]
	s_add_i32 m0, s47, 0x16000
	s_add_u32 s36, s24, s8
	s_addc_u32 s37, s25, s9
	s_add_i32 s48, s47, 0x2000
	global_load_lds_dwordx4 v130, s[10:11]
	s_mov_b32 m0, s47
	s_add_u32 s8, s36, 0x40000
	global_load_lds_dwordx4 v134, s[36:37]
	s_mov_b32 m0, s48
	s_addc_u32 s9, s37, 0
	s_add_i32 s49, s47, 0x4000
	global_load_lds_dwordx4 v132, s[36:37]
	s_mov_b32 m0, s49
	s_add_i32 s66, s47, 0x6000
	global_load_lds_dwordx4 v134, s[8:9]
	s_mov_b32 m0, s66
	v_mov_b32_e32 v131, v1
	global_load_lds_dwordx4 v132, s[8:9]
	v_mov_b32_e32 v135, v1
	v_mov_b32_e32 v133, v1
	s_cmp_eq_u32 s4, 1
	v_lshl_add_u64 v[8:9], s[38:39], 0, v[0:1]
	v_lshl_add_u64 v[6:7], s[38:39], 0, v[130:131]
	v_lshl_add_u64 v[2:3], s[36:37], 0, v[134:135]
	s_cselect_b64 s[8:9], -1, 0
	s_cmp_lg_u32 s4, 1
	v_lshl_add_u64 v[4:5], s[36:37], 0, v[132:133]
	s_cbranch_scc1 .LBB0_502
	s_barrier
; #define PG8_STAGE(bufoff, gbase, voff) do { _Pragma("unroll") for (int _i = 0; _i < 2; ++_i) \
;         __builtin_amdgcn_global_load_lds((const unsigned*)((const char*)(gbase) + (voff)[_i]), (PG8_LAS unsigned*)(lds + (bufoff) + ldsw + _i * 8192), 16, 0, 0); } while (0)
; #define PG8_WAIT_V(n) asm volatile("s_waitcnt vmcnt(" #n ")" ::: "memory")
; #define PG8_BAR __builtin_amdgcn_s_barrier()
; template <class Epi, class Sched, bool ALIGN_EPI = false, bool SP2 = false>
; __device__ __forceinline__ void gemm_phase(PG8_LAS unsigned char* lds, const Gemm g, const Sched& S, const Epi& E) {
;     ...
;     const int aoff = lds_byte(wr * 64 + fr, fq * 8), boff = lds_byte(wc * 32 + fr, fq * 8);
;     ...
;     Unit cur, nxt; int ui = 0;
;     if (!S.next(0, cur)) return;
;     f32x4 acc[2][2][4][2];
; #pragma unroll
;     for (int a = 0; a < 2; ++a)
; #pragma unroll
;         for (int b = 0; b < 2; ++b)
; #pragma unroll
;             for (int m = 0; m < 4; ++m)
; #pragma unroll
;                 for (int n = 0; n < 2; ++n) acc[a][b][m][n] = (f32x4){0.f, 0.f, 0.f, 0.f};
;     bf16x8 At[4][2], B0[2][2], B1[2][2];
;     const char* cA = (const char*)g.A + (size_t)cur.pm * tstep; const char* cB = (const char*)g.Bt + (size_t)cur.pn * tstep;
;     S.a_ready(cur);
;     if constexpr (SP2) {
;         PG8_STAGE(PG8_SB(0, 0), cB, voffB); PG8_STAGE(PG8_SB(0, 1), cB + hstep, voffB); PG8_STAGE(PG8_SA(0, 0), cA, voffA); PG8_STAGE(PG8_SA(0, 1), cA + hstep, voffA);
;         if (wr == 1) PG8_BAR;
;         PG8_WAIT_V(2); PG8_BAR;
;         PG8_STAGE(PG8_SB(1, 0), cB + kstep, voffB); PG8_STAGE(PG8_SA(1, 0), cA + kstep, voffA); PG8_STAGE(PG8_SB(1, 1), cB + hstep + kstep, voffB);
;         PG8_WAIT_V(6); PG8_BAR;
;     } else {
;         PG8_STAGE(PG8_SB(0, 0), cB, voffB); PG8_STAGE(PG8_SA(0, 0), cA, voffA); PG8_STAGE(PG8_SB(0, 1), cB + hstep, voffB); PG8_STAGE(PG8_SA(0, 1), cA + hstep, voffA);
;         if (wr == 1) PG8_BAR;
;         PG8_WAIT_V(4); PG8_BAR;
;         PG8_STAGE(PG8_SB(1, 0), cB + kstep, voffB); PG8_STAGE(PG8_SA(1, 0), cA + kstep, voffA); PG8_STAGE(PG8_SB(1, 1), cB + hstep + kstep, voffB);
;         PG8_WAIT_V(6); PG8_BAR;
.LBB0_502:
	s_lshl_b32 s3, s3, 5
	s_and_b32 s12, s3, 0x60
	s_add_i32 m0, s47, 0x18000
	v_lshl_add_u64 v[8:9], v[8:9], 0, s[40:41]
	s_lshl_b32 s7, s4, 13
	s_lshl_b32 s13, s12, 7
	s_waitcnt vmcnt(2)
	s_barrier
	global_load_lds_dwordx4 v[8:9], off
	v_lshl_add_u64 v[6:7], v[6:7], 0, s[40:41]
	s_add_i32 m0, s47, 0x1a000
	s_add_i32 s68, s47, 0x8000
	s_add_i32 s69, s47, 0xa000
	global_load_lds_dwordx4 v[6:7], off
	v_lshl_add_u64 v[2:3], v[2:3], 0, s[40:41]
	s_mov_b32 m0, s68
	s_add_u32 s10, s38, 0x40080
	global_load_lds_dwordx4 v[2:3], off
	v_lshl_add_u64 v[2:3], v[4:5], 0, s[40:41]
	s_mov_b32 m0, s69
	s_addc_u32 s11, s39, 0
	global_load_lds_dwordx4 v[2:3], off
	s_add_i32 m0, s47, 0x1c000
	v_lshl_add_u64 v[2:3], s[10:11], 0, v[0:1]
	global_load_lds_dwordx4 v[2:3], off
	v_lshl_add_u64 v[2:3], s[10:11], 0, v[130:131]
	s_add_i32 m0, s47, 0x1e000
	s_cmpk_lt_u32 s1, 0x100
	global_load_lds_dwordx4 v[2:3], off
	v_lshrrev_b32_e32 v3, 1, v10
	v_and_b32_e32 v3, 24, v3
	v_and_b32_e32 v2, 15, v10
	v_lshlrev_b32_e32 v4, 1, v3
	v_lshl_or_b32 v142, s4, 6, v2
	v_lshl_or_b32 v2, v2, 6, v4
	v_lshlrev_b32_e32 v4, 2, v10
	v_and_b32_e32 v4, 32, v4
	v_bitop3_b32 v5, v2, s7, v4 bitop3:0xde
	v_mov_b32_e32 v143, v252
	v_lshlrev_b32_e32 v2, 14, v15
	v_and_b32_e32 v2, 0xffff8000, v2
	v_or_b32_e32 v144, s12, v3
	v_lshl_add_u32 v2, v14, 11, v2
	v_and_b32_e32 v3, 1, v15
	v_lshl_or_b32 v2, v3, 6, v2
	v_mov_b32_e32 v136, v232
	v_lshlrev_b32_e32 v2, 14, v11
	v_and_b32_e32 v2, 0xffff8000, v2
	s_waitcnt vmcnt(6)
	v_lshl_add_u32 v2, v12, 11, v2
	v_and_b32_e32 v3, 1, v11
	v_lshl_or_b32 v2, v3, 6, v2
	s_sext_i32_i16 s3, s6
	s_cselect_b64 s[10:11], -1, 0
	s_waitcnt lgkmcnt(0)
	s_ashr_i32 s70, s67, 31
	v_mov_b32_e32 v137, v1
	v_mov_b32_e32 v138, v233
	v_mov_b32_e32 v139, v1
	s_mov_b32 s71, 0
	v_mov_b32_e32 v145, v227
	s_barrier
	s_waitcnt vmcnt(0)
	s_branch .LBB0_505

; #define PG8_STAGE(bufoff, gbase, voff) do { _Pragma("unroll") for (int _i = 0; _i < 2; ++_i) \
;         __builtin_amdgcn_global_load_lds((const unsigned*)((const char*)(gbase) + (voff)[_i]), (PG8_LAS unsigned*)(lds + (bufoff) + ldsw + _i * 8192), 16, 0, 0); } while (0)
; #define PG8_LDA(dst, b, h) do { _Pragma("unroll") for (int m = 0; m < 4; ++m) _Pragma("unroll") for (int k = 0; k < 2; ++k) dst[m][k] = *(const PG8_LAS bf16x8*)(lds + PG8_SA(b, h) + aoff + m * 2048 + k * 1024); } while (0)
; #define PG8_LDB(dst, b, h) do { _Pragma("unroll") for (int n = 0; n < 2; ++n) _Pragma("unroll") for (int k = 0; k < 2; ++k) dst[n][k] = *(const PG8_LAS bf16x8*)(lds + PG8_SB(b, h) + boff + n * 2048 + k * 1024); } while (0)
; #define PG8_MMA(ai, bj, At, Bt) do { __builtin_amdgcn_s_setprio(1); _Pragma("unroll") for (int m = 0; m < 4; ++m) _Pragma("unroll") for (int n = 0; n < 2; ++n) _Pragma("unroll") for (int k = 0; k < 2; ++k) \
;         acc[ai][bj][m][n] = __builtin_amdgcn_mfma_f32_16x16x32_bf16(Bt[n][k], At[m][k], acc[ai][bj][m][n], 0, 0, 0); __builtin_amdgcn_s_setprio(0); } while (0)
; #define PG8_WAIT_V(n) asm volatile("s_waitcnt vmcnt(" #n ")" ::: "memory")
; #define PG8_WAIT_L(n) asm volatile("s_waitcnt lgkmcnt(" #n ")" ::: "memory")
; #define PG8_BAR __builtin_amdgcn_s_barrier()
; template <class Epi, class Sched, bool ALIGN_EPI = false, bool SP2 = false>
; __device__ __forceinline__ void gemm_phase(PG8_LAS unsigned char* lds, const Gemm g, const Sched& S, const Epi& E) {
;     ...
;             const char* a1 = cA + (size_t)(t + 1) * kstep;
;             const char* a2 = last ? nA : cA + (size_t)(t + 2) * kstep; const char* b2 = last ? nB : cB + (size_t)(t + 2) * kstep;
;             const char* a3 = a2 + kstep; const char* b3 = b2 + kstep;
;             if (last && has_next) S.a_ready(nxt);
;             if constexpr (SP2) {
;             PG8_LDB(B0, 0, 0); PG8_LDB(B1, 0, 1); PG8_SCHED; PG8_LDA(At, 0, 0); PG8_STAGE(PG8_SA(1, 1), a1 + hstep, voffA);
;             PG8_WAIT_V(8); PG8_WAIT_L(0); PG8_BAR; PG8_MMA(0, 0, At, B0); PG8_MMA(0, 1, At, B1); PG8_BAR; PG8_SCHED;
;             PG8_LDA(At, 0, 1); PG8_STAGE(PG8_SB(0, 0), b2, voffB); PG8_STAGE(PG8_SB(0, 1), b2 + hstep, voffB); PG8_STAGE(PG8_SA(0, 0), a2, voffA);
;             PG8_WAIT_V(8); PG8_WAIT_L(0); PG8_BAR; PG8_MMA(1, 0, At, B0); PG8_MMA(1, 1, At, B1); PG8_BAR; PG8_SCHED;
.LBB0_508:
	s_add_u32 s1, s36, 0xfffc0080
	s_addc_u32 s35, s37, -1
	s_add_i32 s51, 0, 0x10000
	s_cmp_eq_u32 s33, 12
	s_cselect_b32 s43, s4, s35
	s_cselect_b32 s42, s15, s1
	v_add_u32_e32 v140, s51, v143
	v_add_u32_e32 v250, s51, v226
	s_cselect_b32 s39, s13, s23
	s_cselect_b32 s38, s18, s19
	s_add_i32 s1, 0, 0x14000
	ds_read_b128 v[146:149], v140
	ds_read_b128 v[150:153], v250
	ds_read_b128 v[154:157], v140 offset:2048
	ds_read_b128 v[158:161], v250 offset:2048
	v_add_u32_e32 v140, s1, v143
	v_add_u32_e32 v251, s1, v226
	ds_read_b128 v[162:165], v140
	ds_read_b128 v[166:169], v251
	ds_read_b128 v[170:173], v140 offset:2048
	ds_read_b128 v[174:177], v251 offset:2048
	v_lshl_add_u64 v[140:141], s[36:37], 0, v[136:137]
	s_add_i32 m0, s47, 0xc000
	ds_read_b128 v[178:181], v145
	ds_read_b128 v[182:185], v225
	ds_read_b128 v[186:189], v145 offset:2048
	ds_read_b128 v[190:193], v225 offset:2048
	ds_read_b128 v[194:197], v145 offset:4096
	ds_read_b128 v[198:201], v225 offset:4096
	ds_read_b128 v[202:205], v145 offset:6144
	ds_read_b128 v[206:209], v225 offset:6144
	global_load_lds_dwordx4 v[140:141], off
	v_lshl_add_u64 v[140:141], s[36:37], 0, v[138:139]
	s_add_i32 m0, s47, 0xe000
	s_nop 0
	global_load_lds_dwordx4 v[140:141], off
	s_waitcnt vmcnt(8)
	s_waitcnt lgkmcnt(0)
	s_barrier
	s_setprio 1
	s_waitcnt lgkmcnt(0)
	v_mfma_f32_16x16x32_bf16 v[126:129], v[146:149], v[178:181], v[126:129]
	v_mfma_f32_16x16x32_bf16 v[118:121], v[154:157], v[178:181], v[118:121]
	v_mfma_f32_16x16x32_bf16 v[110:113], v[146:149], v[186:189], v[110:113]
	v_mfma_f32_16x16x32_bf16 v[102:105], v[154:157], v[186:189], v[102:105]
	v_mfma_f32_16x16x32_bf16 v[94:97], v[146:149], v[194:197], v[94:97]
	v_mfma_f32_16x16x32_bf16 v[86:89], v[154:157], v[194:197], v[86:89]
	v_mfma_f32_16x16x32_bf16 v[78:81], v[146:149], v[202:205], v[78:81]
	v_mfma_f32_16x16x32_bf16 v[70:73], v[154:157], v[202:205], v[70:73]
	v_mfma_f32_16x16x32_bf16 v[126:129], v[150:153], v[182:185], v[126:129]
	v_mfma_f32_16x16x32_bf16 v[118:121], v[158:161], v[182:185], v[118:121]
	v_mfma_f32_16x16x32_bf16 v[110:113], v[150:153], v[190:193], v[110:113]
	v_mfma_f32_16x16x32_bf16 v[102:105], v[158:161], v[190:193], v[102:105]
	v_mfma_f32_16x16x32_bf16 v[94:97], v[150:153], v[198:201], v[94:97]
	v_mfma_f32_16x16x32_bf16 v[86:89], v[158:161], v[198:201], v[86:89]
	v_mfma_f32_16x16x32_bf16 v[78:81], v[150:153], v[206:209], v[78:81]
	v_mfma_f32_16x16x32_bf16 v[70:73], v[158:161], v[206:209], v[70:73]
	s_setprio 0
	s_setprio 1
	v_mfma_f32_16x16x32_bf16 v[122:125], v[162:165], v[178:181], v[122:125]
	v_mfma_f32_16x16x32_bf16 v[114:117], v[170:173], v[178:181], v[114:117]
	v_mfma_f32_16x16x32_bf16 v[106:109], v[162:165], v[186:189], v[106:109]
	v_mfma_f32_16x16x32_bf16 v[98:101], v[170:173], v[186:189], v[98:101]
	v_mfma_f32_16x16x32_bf16 v[90:93], v[162:165], v[194:197], v[90:93]
	v_mfma_f32_16x16x32_bf16 v[82:85], v[170:173], v[194:197], v[82:85]
	v_mfma_f32_16x16x32_bf16 v[74:77], v[162:165], v[202:205], v[74:77]
	v_mfma_f32_16x16x32_bf16 v[66:69], v[170:173], v[202:205], v[66:69]
	v_mfma_f32_16x16x32_bf16 v[122:125], v[166:169], v[182:185], v[122:125]
	v_mfma_f32_16x16x32_bf16 v[114:117], v[174:177], v[182:185], v[114:117]
	v_mfma_f32_16x16x32_bf16 v[106:109], v[166:169], v[190:193], v[106:109]
	v_mfma_f32_16x16x32_bf16 v[98:101], v[174:177], v[190:193], v[98:101]
	v_mfma_f32_16x16x32_bf16 v[90:93], v[166:169], v[198:201], v[90:93]
	v_mfma_f32_16x16x32_bf16 v[82:85], v[174:177], v[198:201], v[82:85]
	v_mfma_f32_16x16x32_bf16 v[74:77], v[166:169], v[206:209], v[74:77]
	v_mfma_f32_16x16x32_bf16 v[66:69], v[174:177], v[206:209], v[66:69]
	s_setprio 0
	s_barrier
	s_add_i32 s35, s51, s45
	v_lshl_add_u64 v[140:141], s[38:39], 0, v[0:1]
	s_mov_b32 m0, s35
	ds_read_b128 v[178:181], v145 offset:16384
	ds_read_b128 v[182:185], v225 offset:16384
	ds_read_b128 v[186:189], v145 offset:18432
	ds_read_b128 v[190:193], v225 offset:18432
	ds_read_b128 v[194:197], v145 offset:20480
	ds_read_b128 v[198:201], v225 offset:20480
	ds_read_b128 v[202:205], v145 offset:22528
	ds_read_b128 v[206:209], v225 offset:22528
	global_load_lds_dwordx4 v[140:141], off
	s_add_i32 m0, s35, 0x2000
	s_add_u32 s72, s38, 0x40000
	v_lshl_add_u64 v[210:211], s[38:39], 0, v[130:131]
	s_addc_u32 s73, s39, 0
	s_add_i32 s1, s1, s45
	global_load_lds_dwordx4 v[210:211], off
	v_lshl_add_u64 v[212:213], s[72:73], 0, v[0:1]
	s_mov_b32 m0, s1
	v_lshl_add_u64 v[214:215], s[42:43], 0, v[132:133]
	global_load_lds_dwordx4 v[212:213], off
	v_lshl_add_u64 v[212:213], s[72:73], 0, v[130:131]
	s_add_i32 m0, s1, 0x2000
	s_nop 0
	global_load_lds_dwordx4 v[212:213], off
	v_lshl_add_u64 v[212:213], s[42:43], 0, v[134:135]
	s_mov_b32 m0, s47
	s_nop 0
	global_load_lds_dwordx4 v[212:213], off
	s_mov_b32 m0, s48
	s_nop 0
	global_load_lds_dwordx4 v[214:215], off
	s_waitcnt vmcnt(8)
	s_waitcnt lgkmcnt(0)
	s_barrier
; #define PG8_STAGE(bufoff, gbase, voff) do { _Pragma("unroll") for (int _i = 0; _i < 2; ++_i) \
;         __builtin_amdgcn_global_load_lds((const unsigned*)((const char*)(gbase) + (voff)[_i]), (PG8_LAS unsigned*)(lds + (bufoff) + ldsw + _i * 8192), 16, 0, 0); } while (0)
; #define PG8_LDA(dst, b, h) do { _Pragma("unroll") for (int m = 0; m < 4; ++m) _Pragma("unroll") for (int k = 0; k < 2; ++k) dst[m][k] = *(const PG8_LAS bf16x8*)(lds + PG8_SA(b, h) + aoff + m * 2048 + k * 1024); } while (0)
; #define PG8_LDB(dst, b, h) do { _Pragma("unroll") for (int n = 0; n < 2; ++n) _Pragma("unroll") for (int k = 0; k < 2; ++k) dst[n][k] = *(const PG8_LAS bf16x8*)(lds + PG8_SB(b, h) + boff + n * 2048 + k * 1024); } while (0)
; #define PG8_MMA(ai, bj, At, Bt) do { __builtin_amdgcn_s_setprio(1); _Pragma("unroll") for (int m = 0; m < 4; ++m) _Pragma("unroll") for (int n = 0; n < 2; ++n) _Pragma("unroll") for (int k = 0; k < 2; ++k) \
;         acc[ai][bj][m][n] = __builtin_amdgcn_mfma_f32_16x16x32_bf16(Bt[n][k], At[m][k], acc[ai][bj][m][n], 0, 0, 0); __builtin_amdgcn_s_setprio(0); } while (0)
; #define PG8_WAIT_V(n) asm volatile("s_waitcnt vmcnt(" #n ")" ::: "memory")
; #define PG8_WAIT_L(n) asm volatile("s_waitcnt lgkmcnt(" #n ")" ::: "memory")
; #define PG8_BAR __builtin_amdgcn_s_barrier()
; #define PG8_SCHED __builtin_amdgcn_sched_barrier(0)
; template <class Epi, class Sched, bool ALIGN_EPI = false, bool SP2 = false>
; __device__ __forceinline__ void gemm_phase(PG8_LAS unsigned char* lds, const Gemm g, const Sched& S, const Epi& E) {
;     ...
;             PG8_WAIT_V(8); PG8_WAIT_L(0); PG8_BAR; PG8_MMA(1, 0, At, B0); PG8_MMA(1, 1, At, B1); PG8_BAR; PG8_SCHED;
;             PG8_LDB(B0, 1, 0); PG8_LDB(B1, 1, 1); PG8_SCHED; PG8_LDA(At, 1, 0); PG8_STAGE(PG8_SA(0, 1), a2 + hstep, voffA);
;             PG8_WAIT_V(8); PG8_WAIT_L(0); PG8_BAR; PG8_MMA(0, 0, At, B0); PG8_MMA(0, 1, At, B1); PG8_BAR; PG8_SCHED;
	s_setprio 1
	s_waitcnt lgkmcnt(0)
	v_mfma_f32_16x16x32_bf16 v[62:65], v[146:149], v[178:181], v[62:65]
	v_mfma_f32_16x16x32_bf16 v[54:57], v[154:157], v[178:181], v[54:57]
	v_mfma_f32_16x16x32_bf16 v[46:49], v[146:149], v[186:189], v[46:49]
	v_mfma_f32_16x16x32_bf16 v[38:41], v[154:157], v[186:189], v[38:41]
	v_mfma_f32_16x16x32_bf16 v[30:33], v[146:149], v[194:197], v[30:33]
	v_mfma_f32_16x16x32_bf16 v[22:25], v[154:157], v[194:197], v[22:25]
	v_mfma_f32_16x16x32_bf16 v[14:17], v[146:149], v[202:205], v[14:17]
	v_mfma_f32_16x16x32_bf16 v[6:9], v[154:157], v[202:205], v[6:9]
	v_mfma_f32_16x16x32_bf16 v[62:65], v[150:153], v[182:185], v[62:65]
	v_mfma_f32_16x16x32_bf16 v[54:57], v[158:161], v[182:185], v[54:57]
	v_mfma_f32_16x16x32_bf16 v[46:49], v[150:153], v[190:193], v[46:49]
	v_mfma_f32_16x16x32_bf16 v[38:41], v[158:161], v[190:193], v[38:41]
	v_mfma_f32_16x16x32_bf16 v[30:33], v[150:153], v[198:201], v[30:33]
	v_mfma_f32_16x16x32_bf16 v[22:25], v[158:161], v[198:201], v[22:25]
	v_mfma_f32_16x16x32_bf16 v[14:17], v[150:153], v[206:209], v[14:17]
	v_mfma_f32_16x16x32_bf16 v[6:9], v[158:161], v[206:209], v[6:9]
	s_setprio 0
	s_setprio 1
	v_mfma_f32_16x16x32_bf16 v[58:61], v[162:165], v[178:181], v[58:61]
	v_mfma_f32_16x16x32_bf16 v[50:53], v[170:173], v[178:181], v[50:53]
	v_mfma_f32_16x16x32_bf16 v[42:45], v[162:165], v[186:189], v[42:45]
	v_mfma_f32_16x16x32_bf16 v[34:37], v[170:173], v[186:189], v[34:37]
	v_mfma_f32_16x16x32_bf16 v[26:29], v[162:165], v[194:197], v[26:29]
	v_mfma_f32_16x16x32_bf16 v[18:21], v[170:173], v[194:197], v[18:21]
	v_mfma_f32_16x16x32_bf16 v[10:13], v[162:165], v[202:205], v[10:13]
	v_mfma_f32_16x16x32_bf16 v[2:5], v[170:173], v[202:205], v[2:5]
	v_mfma_f32_16x16x32_bf16 v[58:61], v[166:169], v[182:185], v[58:61]
	v_mfma_f32_16x16x32_bf16 v[50:53], v[174:177], v[182:185], v[50:53]
	v_mfma_f32_16x16x32_bf16 v[42:45], v[166:169], v[190:193], v[42:45]
	v_mfma_f32_16x16x32_bf16 v[34:37], v[174:177], v[190:193], v[34:37]
	v_mfma_f32_16x16x32_bf16 v[26:29], v[166:169], v[198:201], v[26:29]
	v_mfma_f32_16x16x32_bf16 v[18:21], v[174:177], v[198:201], v[18:21]
	v_mfma_f32_16x16x32_bf16 v[10:13], v[166:169], v[206:209], v[10:13]
	v_mfma_f32_16x16x32_bf16 v[2:5], v[174:177], v[206:209], v[2:5]
	s_setprio 0
	s_barrier
	s_add_i32 s1, 0, 0x18000
	s_add_i32 s35, 0, 0x1c000
	v_add_u32_e32 v158, s1, v143
	v_add_u32_e32 v250, s1, v226
	v_add_u32_e32 v174, s35, v143
	v_add_u32_e32 v251, s35, v226
	ds_read_b128 v[146:149], v158
	ds_read_b128 v[150:153], v250
	ds_read_b128 v[154:157], v158 offset:2048
	ds_read_b128 v[158:161], v250 offset:2048
	ds_read_b128 v[162:165], v174
	ds_read_b128 v[166:169], v251
	ds_read_b128 v[170:173], v174 offset:2048
	ds_read_b128 v[174:177], v251 offset:2048
	s_add_u32 s42, s42, 0x40000
	s_addc_u32 s43, s43, 0
	s_mov_b32 m0, s49
	v_lshl_add_u64 v[216:217], s[42:43], 0, v[134:135]
	ds_read_b128 v[178:181], v145 offset:32768
	ds_read_b128 v[182:185], v225 offset:32768
	ds_read_b128 v[186:189], v145 offset:34816
	ds_read_b128 v[190:193], v225 offset:34816
	ds_read_b128 v[194:197], v145 offset:36864
	ds_read_b128 v[198:201], v225 offset:36864
	ds_read_b128 v[202:205], v145 offset:38912
	ds_read_b128 v[206:209], v225 offset:38912
	global_load_lds_dwordx4 v[216:217], off
	v_lshl_add_u64 v[216:217], s[42:43], 0, v[132:133]
	s_mov_b32 m0, s66
	s_nop 0
	global_load_lds_dwordx4 v[216:217], off
	s_waitcnt vmcnt(8)
	s_waitcnt lgkmcnt(0)
	s_barrier
	s_setprio 1
	s_waitcnt lgkmcnt(0)
	v_mfma_f32_16x16x32_bf16 v[126:129], v[146:149], v[178:181], v[126:129]
	v_mfma_f32_16x16x32_bf16 v[118:121], v[154:157], v[178:181], v[118:121]
	v_mfma_f32_16x16x32_bf16 v[110:113], v[146:149], v[186:189], v[110:113]
	v_mfma_f32_16x16x32_bf16 v[102:105], v[154:157], v[186:189], v[102:105]
	v_mfma_f32_16x16x32_bf16 v[94:97], v[146:149], v[194:197], v[94:97]
	v_mfma_f32_16x16x32_bf16 v[86:89], v[154:157], v[194:197], v[86:89]
	v_mfma_f32_16x16x32_bf16 v[78:81], v[146:149], v[202:205], v[78:81]
	v_mfma_f32_16x16x32_bf16 v[70:73], v[154:157], v[202:205], v[70:73]
	v_mfma_f32_16x16x32_bf16 v[126:129], v[150:153], v[182:185], v[126:129]
	v_mfma_f32_16x16x32_bf16 v[118:121], v[158:161], v[182:185], v[118:121]
	v_mfma_f32_16x16x32_bf16 v[110:113], v[150:153], v[190:193], v[110:113]
	v_mfma_f32_16x16x32_bf16 v[102:105], v[158:161], v[190:193], v[102:105]
	v_mfma_f32_16x16x32_bf16 v[94:97], v[150:153], v[198:201], v[94:97]
	v_mfma_f32_16x16x32_bf16 v[86:89], v[158:161], v[198:201], v[86:89]
	v_mfma_f32_16x16x32_bf16 v[78:81], v[150:153], v[206:209], v[78:81]
	v_mfma_f32_16x16x32_bf16 v[70:73], v[158:161], v[206:209], v[70:73]
	s_setprio 0
	s_setprio 1
	v_mfma_f32_16x16x32_bf16 v[122:125], v[162:165], v[178:181], v[122:125]
	v_mfma_f32_16x16x32_bf16 v[114:117], v[170:173], v[178:181], v[114:117]
	v_mfma_f32_16x16x32_bf16 v[106:109], v[162:165], v[186:189], v[106:109]
	v_mfma_f32_16x16x32_bf16 v[98:101], v[170:173], v[186:189], v[98:101]
	v_mfma_f32_16x16x32_bf16 v[90:93], v[162:165], v[194:197], v[90:93]
	v_mfma_f32_16x16x32_bf16 v[82:85], v[170:173], v[194:197], v[82:85]
	v_mfma_f32_16x16x32_bf16 v[74:77], v[162:165], v[202:205], v[74:77]
	v_mfma_f32_16x16x32_bf16 v[66:69], v[170:173], v[202:205], v[66:69]
	v_mfma_f32_16x16x32_bf16 v[122:125], v[166:169], v[182:185], v[122:125]
	v_mfma_f32_16x16x32_bf16 v[114:117], v[174:177], v[182:185], v[114:117]
	v_mfma_f32_16x16x32_bf16 v[106:109], v[166:169], v[190:193], v[106:109]
	v_mfma_f32_16x16x32_bf16 v[98:101], v[174:177], v[190:193], v[98:101]
	v_mfma_f32_16x16x32_bf16 v[90:93], v[166:169], v[198:201], v[90:93]
	v_mfma_f32_16x16x32_bf16 v[82:85], v[174:177], v[198:201], v[82:85]
	v_mfma_f32_16x16x32_bf16 v[74:77], v[166:169], v[206:209], v[74:77]
	v_mfma_f32_16x16x32_bf16 v[66:69], v[174:177], v[206:209], v[66:69]
	s_setprio 0
	s_barrier
; #define PG8_STAGE(bufoff, gbase, voff) do { _Pragma("unroll") for (int _i = 0; _i < 2; ++_i) \
;         __builtin_amdgcn_global_load_lds((const unsigned*)((const char*)(gbase) + (voff)[_i]), (PG8_LAS unsigned*)(lds + (bufoff) + ldsw + _i * 8192), 16, 0, 0); } while (0)
; #define PG8_LDA(dst, b, h) do { _Pragma("unroll") for (int m = 0; m < 4; ++m) _Pragma("unroll") for (int k = 0; k < 2; ++k) dst[m][k] = *(const PG8_LAS bf16x8*)(lds + PG8_SA(b, h) + aoff + m * 2048 + k * 1024); } while (0)
; #define PG8_MMA(ai, bj, At, Bt) do { __builtin_amdgcn_s_setprio(1); _Pragma("unroll") for (int m = 0; m < 4; ++m) _Pragma("unroll") for (int n = 0; n < 2; ++n) _Pragma("unroll") for (int k = 0; k < 2; ++k) \
;         acc[ai][bj][m][n] = __builtin_amdgcn_mfma_f32_16x16x32_bf16(Bt[n][k], At[m][k], acc[ai][bj][m][n], 0, 0, 0); __builtin_amdgcn_s_setprio(0); } while (0)
; #define PG8_WAIT_V(n) asm volatile("s_waitcnt vmcnt(" #n ")" ::: "memory")
; #define PG8_WAIT_L(n) asm volatile("s_waitcnt lgkmcnt(" #n ")" ::: "memory")
; #define PG8_BAR __builtin_amdgcn_s_barrier()
; #define PG8_SCHED __builtin_amdgcn_sched_barrier(0)
; template <class Epi, class Sched, bool ALIGN_EPI = false, bool SP2 = false>
; __device__ __forceinline__ void gemm_phase(PG8_LAS unsigned char* lds, const Gemm g, const Sched& S, const Epi& E) {
;     ...
;             PG8_LDA(At, 1, 1); PG8_STAGE(PG8_SB(1, 0), b3, voffB); PG8_STAGE(PG8_SB(1, 1), b3 + hstep, voffB); PG8_STAGE(PG8_SA(1, 0), a3, voffA);
;             PG8_WAIT_V(8); PG8_WAIT_L(0); PG8_BAR; PG8_MMA(1, 0, At, B0); PG8_MMA(1, 1, At, B1); PG8_BAR; PG8_SCHED;
	s_add_i32 s1, s1, s45
	v_lshl_add_u64 v[140:141], v[140:141], 0, s[40:41]
	s_mov_b32 m0, s1
	ds_read_b128 v[178:181], v145 offset:49152
	ds_read_b128 v[182:185], v225 offset:49152
	ds_read_b128 v[186:189], v145 offset:51200
	ds_read_b128 v[190:193], v225 offset:51200
	ds_read_b128 v[194:197], v145 offset:53248
	ds_read_b128 v[198:201], v225 offset:53248
	ds_read_b128 v[202:205], v145 offset:55296
	ds_read_b128 v[206:209], v225 offset:55296
	global_load_lds_dwordx4 v[140:141], off
	s_add_i32 m0, s1, 0x2000
	s_add_u32 s38, s38, 0x40080
	v_lshl_add_u64 v[140:141], v[210:211], 0, s[40:41]
	s_addc_u32 s39, s39, 0
	s_add_i32 s1, s35, s45
	global_load_lds_dwordx4 v[140:141], off
	v_lshl_add_u64 v[140:141], s[38:39], 0, v[0:1]
	s_mov_b32 m0, s1
	s_nop 0
	global_load_lds_dwordx4 v[140:141], off
	v_lshl_add_u64 v[140:141], s[38:39], 0, v[130:131]
	s_add_i32 m0, s1, 0x2000
	s_nop 0
	global_load_lds_dwordx4 v[140:141], off
	v_lshl_add_u64 v[140:141], v[212:213], 0, s[40:41]
	s_mov_b32 m0, s68
	s_nop 0
	global_load_lds_dwordx4 v[140:141], off
	v_lshl_add_u64 v[140:141], v[214:215], 0, s[40:41]
	s_mov_b32 m0, s69
	s_nop 0
	global_load_lds_dwordx4 v[140:141], off
	s_waitcnt vmcnt(8)
	s_waitcnt lgkmcnt(0)
	s_barrier
	s_setprio 1
	s_waitcnt lgkmcnt(0)
	v_mfma_f32_16x16x32_bf16 v[62:65], v[146:149], v[178:181], v[62:65]
	v_mfma_f32_16x16x32_bf16 v[54:57], v[154:157], v[178:181], v[54:57]
	v_mfma_f32_16x16x32_bf16 v[46:49], v[146:149], v[186:189], v[46:49]
	v_mfma_f32_16x16x32_bf16 v[38:41], v[154:157], v[186:189], v[38:41]
	v_mfma_f32_16x16x32_bf16 v[30:33], v[146:149], v[194:197], v[30:33]
	v_mfma_f32_16x16x32_bf16 v[22:25], v[154:157], v[194:197], v[22:25]
	v_mfma_f32_16x16x32_bf16 v[14:17], v[146:149], v[202:205], v[14:17]
	v_mfma_f32_16x16x32_bf16 v[6:9], v[154:157], v[202:205], v[6:9]
	v_mfma_f32_16x16x32_bf16 v[62:65], v[150:153], v[182:185], v[62:65]
	v_mfma_f32_16x16x32_bf16 v[54:57], v[158:161], v[182:185], v[54:57]
	v_mfma_f32_16x16x32_bf16 v[46:49], v[150:153], v[190:193], v[46:49]
	v_mfma_f32_16x16x32_bf16 v[38:41], v[158:161], v[190:193], v[38:41]
	v_mfma_f32_16x16x32_bf16 v[30:33], v[150:153], v[198:201], v[30:33]
	v_mfma_f32_16x16x32_bf16 v[22:25], v[158:161], v[198:201], v[22:25]
	v_mfma_f32_16x16x32_bf16 v[14:17], v[150:153], v[206:209], v[14:17]
	v_mfma_f32_16x16x32_bf16 v[6:9], v[158:161], v[206:209], v[6:9]
	s_setprio 0
	s_setprio 1
	v_mfma_f32_16x16x32_bf16 v[58:61], v[162:165], v[178:181], v[58:61]
	v_mfma_f32_16x16x32_bf16 v[50:53], v[170:173], v[178:181], v[50:53]
	v_mfma_f32_16x16x32_bf16 v[42:45], v[162:165], v[186:189], v[42:45]
	v_mfma_f32_16x16x32_bf16 v[34:37], v[170:173], v[186:189], v[34:37]
	v_mfma_f32_16x16x32_bf16 v[26:29], v[162:165], v[194:197], v[26:29]
	v_mfma_f32_16x16x32_bf16 v[18:21], v[170:173], v[194:197], v[18:21]
	v_mfma_f32_16x16x32_bf16 v[10:13], v[162:165], v[202:205], v[10:13]
	v_mfma_f32_16x16x32_bf16 v[2:5], v[170:173], v[202:205], v[2:5]
	v_mfma_f32_16x16x32_bf16 v[58:61], v[166:169], v[182:185], v[58:61]
	v_mfma_f32_16x16x32_bf16 v[50:53], v[174:177], v[182:185], v[50:53]
	v_mfma_f32_16x16x32_bf16 v[42:45], v[166:169], v[190:193], v[42:45]
	v_mfma_f32_16x16x32_bf16 v[34:37], v[174:177], v[190:193], v[34:37]
	v_mfma_f32_16x16x32_bf16 v[26:29], v[166:169], v[198:201], v[26:29]
	v_mfma_f32_16x16x32_bf16 v[18:21], v[174:177], v[198:201], v[18:21]
	v_mfma_f32_16x16x32_bf16 v[10:13], v[166:169], v[206:209], v[10:13]
	v_mfma_f32_16x16x32_bf16 v[2:5], v[174:177], v[206:209], v[2:5]
	s_setprio 0
	s_barrier
	s_add_i32 s33, s33, 2
	s_add_u32 s36, s36, 0x100
	s_addc_u32 s37, s37, 0
	s_add_u32 s19, s19, 0x100
	s_addc_u32 s23, s23, 0
	s_cmp_gt_u32 s33, 13
	s_cbranch_scc0 .LBB0_508
	s_and_b64 vcc, exec, s[10:11]
	s_cbranch_vccz .LBB0_511
	s_barrier
